# lora-2 stage of the scan producers rewritten: 10 MFMAs back to back, packed-f32 sigmoid math without branches; consumer lane constants computed once; no barrier between phases 19 and 20
# speedup vs baseline: 1.0144x; 1.0023x over previous
.LBB0_808:
	s_add_i32 s31, s30, -1
	s_and_b32 s8, s31, 1
	s_mul_i32 s4, s8, 0xc300
	s_add_i32 s5, s4, 0
	s_bitcmp1_b32 s30, 0
	s_cselect_b32 s4, 0xc300, 0
	v_lshl_add_u32 v124, v101, 2, s5
	v_lshl_add_u32 v123, v102, 2, s5
	v_lshl_add_u32 v122, s8, 12, v111
	s_and_saveexec_b64 s[8:9], s[42:43]
	s_xor_b64 s[18:19], exec, s[8:9]
	s_cbranch_execz .LBB0_810
	s_setprio 3
	s_cmp_lg_u32 s20, 0
	s_cbranch_scc1 .Lscan_c_nosetup
	v_and_b32_e32 v214, 15, v166
	v_lshlrev_b32_e32 v213, 4, v214
	v_lshrrev_b32_e32 v218, 1, v214
	v_cmp_eq_u32_e64 s[48:49], 0, v218
	v_cmp_eq_u32_e64 s[50:51], 1, v218
	v_cmp_eq_u32_e64 s[52:53], 2, v218
	v_cmp_eq_u32_e64 s[54:55], 3, v218
	v_cmp_eq_u32_e64 s[56:57], 4, v218
	v_cmp_eq_u32_e64 s[58:59], 5, v218
	v_cmp_eq_u32_e64 s[60:61], 6, v218
	v_cmp_eq_u32_e64 s[62:63], 7, v218
	v_lshlrev_b32_e32 v217, 7, v218
	v_lshrrev_b32_e32 v218, 4, v166
	v_and_b32_e32 v219, 1, v166
	v_lshl_or_b32 v218, v218, 1, v219
	v_lshl_add_u32 v217, v218, 2, v217
	v_add_u32_e32 v217, 0x18600, v217
	v_mul_u32_u24_e32 v215, 0x90, v218
	v_xor_b32_e32 v219, 1, v218
	v_mul_u32_u24_e32 v216, 0x90, v219
	.Lscan_c_nosetup:
	v_add_u32_e32 v208, s5, v213
	ds_read_b128 v[128:131], v208 offset:0
	ds_read_b128 v[132:135], v208 offset:256
	v_add_u32_e32 v209, s5, v215
	v_add_u32_e32 v210, s5, v216
	ds_read_b128 v[136:139], v208 offset:16384
	ds_read_b128 v[140:143], v208 offset:24576
	ds_read_b128 v[144:147], v208 offset:32768
	v_mov_b32_e32 v211, s5
	ds_read_b128 v[176:179], v209 offset:40960
	ds_read_b128 v[180:183], v210 offset:40960
	ds_read_b128 v[184:187], v211 offset:49664
	ds_read_b128 v[188:191], v211 offset:49680
	ds_read_b128 v[148:151], v208 offset:512
	ds_read_b128 v[152:155], v208 offset:768
	ds_read_b128 v[156:159], v208 offset:16640
	ds_read_b128 v[168:171], v208 offset:24832
	ds_read_b128 v[172:175], v208 offset:33024
	v_lshrrev_b32_e32 v214, 2, v211
	v_and_b32_e32 v214, 0x1000, v214
	v_add_u32_e32 v212, v217, v214
	s_waitcnt lgkmcnt(5)
	v_pk_mul_f32 v[42:43], v[34:35], v[128:129] op_sel_hi:[0,1]
	v_pk_mul_f32 v[44:45], v[38:39], v[128:129] op_sel_hi:[0,1]
	v_pk_fma_f32 v[42:43], v[34:35], v[130:131], v[42:43] op_sel:[1,0,0]
	v_pk_fma_f32 v[44:45], v[38:39], v[130:131], v[44:45] op_sel:[1,0,0]
	v_pk_fma_f32 v[42:43], v[36:37], v[132:133], v[42:43] op_sel_hi:[0,1,1]
	v_pk_fma_f32 v[44:45], v[40:41], v[132:133], v[44:45] op_sel_hi:[0,1,1]
	v_pk_fma_f32 v[42:43], v[36:37], v[134:135], v[42:43] op_sel:[1,0,0]
	v_pk_fma_f32 v[44:45], v[40:41], v[134:135], v[44:45] op_sel:[1,0,0]
	v_pk_mul_f32 v[46:47], v[144:145], v[176:177] op_sel_hi:[1,0]
	v_pk_mul_f32 v[48:49], v[146:147], v[176:177] op_sel_hi:[1,0]
	v_add_f32_dpp v42, v44, v42 quad_perm:[1,0,3,2] row_mask:0xf bank_mask:0xf bound_ctrl:1
	v_add_f32_dpp v43, v45, v43 quad_perm:[1,0,3,2] row_mask:0xf bank_mask:0xf bound_ctrl:1
	v_pk_mul_f32 v[50:51], v[144:145], v[180:181] op_sel_hi:[1,0]
	v_add_f32_dpp v42, v42, v42 quad_perm:[2,3,0,1] row_mask:0xf bank_mask:0xf bound_ctrl:1
	v_add_f32_dpp v43, v43, v43 quad_perm:[2,3,0,1] row_mask:0xf bank_mask:0xf bound_ctrl:1
	v_pk_mul_f32 v[52:53], v[146:147], v[180:181] op_sel_hi:[1,0]
	v_add_f32_dpp v42, v42, v42 row_ror:4 row_mask:0xf bank_mask:0xf bound_ctrl:1
	v_add_f32_dpp v43, v43, v43 row_ror:4 row_mask:0xf bank_mask:0xf bound_ctrl:1
	ds_read_b128 v[128:131], v208 offset:1024
	v_add_f32_dpp v42, v42, v42 row_ror:8 row_mask:0xf bank_mask:0xf bound_ctrl:1
	v_add_f32_dpp v43, v43, v43 row_ror:8 row_mask:0xf bank_mask:0xf bound_ctrl:1
	v_pk_fma_f32 v[46:47], v[140:141], v[42:43], v[46:47] op_sel_hi:[1,0,1]
	v_mov_b32_dpp v54, v42 quad_perm:[1,0,3,2] row_mask:0xf bank_mask:0xf bound_ctrl:1
	v_pk_fma_f32 v[48:49], v[142:143], v[42:43], v[48:49] op_sel_hi:[1,0,1]
	v_fmac_f32_e32 v43, v184, v42
	v_pk_fma_f32 v[34:35], v[34:35], v[136:137], v[46:47]
	v_pk_fma_f32 v[36:37], v[36:37], v[138:139], v[48:49]
	v_pk_fma_f32 v[50:51], v[140:141], v[54:55], v[50:51] op_sel_hi:[1,0,1]
	v_pk_fma_f32 v[52:53], v[142:143], v[54:55], v[52:53] op_sel_hi:[1,0,1]
	v_fmac_f32_e32 v43, v176, v185
	v_pk_fma_f32 v[38:39], v[38:39], v[136:137], v[50:51]
	v_pk_fma_f32 v[40:41], v[40:41], v[138:139], v[52:53]
	v_cndmask_b32_e64 v55, 0, v43, s[48:49]
	ds_read_b128 v[132:135], v208 offset:1280
	ds_read_b128 v[136:139], v208 offset:16896
	ds_read_b128 v[140:143], v208 offset:25088
	ds_read_b128 v[144:147], v208 offset:33280
	s_waitcnt lgkmcnt(5)
	v_pk_mul_f32 v[42:43], v[34:35], v[148:149] op_sel_hi:[0,1]
	v_pk_mul_f32 v[44:45], v[38:39], v[148:149] op_sel_hi:[0,1]
	v_pk_fma_f32 v[42:43], v[34:35], v[150:151], v[42:43] op_sel:[1,0,0]
	v_pk_fma_f32 v[44:45], v[38:39], v[150:151], v[44:45] op_sel:[1,0,0]
	v_pk_fma_f32 v[42:43], v[36:37], v[152:153], v[42:43] op_sel_hi:[0,1,1]
	v_pk_fma_f32 v[44:45], v[40:41], v[152:153], v[44:45] op_sel_hi:[0,1,1]
	v_pk_fma_f32 v[42:43], v[36:37], v[154:155], v[42:43] op_sel:[1,0,0]
	v_pk_fma_f32 v[44:45], v[40:41], v[154:155], v[44:45] op_sel:[1,0,0]
	v_pk_mul_f32 v[46:47], v[172:173], v[176:177] op_sel:[0,1]
	v_pk_mul_f32 v[48:49], v[174:175], v[176:177] op_sel:[0,1]
	v_add_f32_dpp v42, v44, v42 quad_perm:[1,0,3,2] row_mask:0xf bank_mask:0xf bound_ctrl:1
	v_add_f32_dpp v43, v45, v43 quad_perm:[1,0,3,2] row_mask:0xf bank_mask:0xf bound_ctrl:1
	v_pk_mul_f32 v[50:51], v[172:173], v[180:181] op_sel:[0,1]
	v_add_f32_dpp v42, v42, v42 quad_perm:[2,3,0,1] row_mask:0xf bank_mask:0xf bound_ctrl:1
	v_add_f32_dpp v43, v43, v43 quad_perm:[2,3,0,1] row_mask:0xf bank_mask:0xf bound_ctrl:1
	v_pk_mul_f32 v[52:53], v[174:175], v[180:181] op_sel:[0,1]
	v_add_f32_dpp v42, v42, v42 row_ror:4 row_mask:0xf bank_mask:0xf bound_ctrl:1
	v_add_f32_dpp v43, v43, v43 row_ror:4 row_mask:0xf bank_mask:0xf bound_ctrl:1
	ds_read_b128 v[148:151], v208 offset:1536
	v_add_f32_dpp v42, v42, v42 row_ror:8 row_mask:0xf bank_mask:0xf bound_ctrl:1
	v_add_f32_dpp v43, v43, v43 row_ror:8 row_mask:0xf bank_mask:0xf bound_ctrl:1
	v_pk_fma_f32 v[46:47], v[168:169], v[42:43], v[46:47] op_sel_hi:[1,0,1]
	v_mov_b32_dpp v54, v42 quad_perm:[1,0,3,2] row_mask:0xf bank_mask:0xf bound_ctrl:1
	v_pk_fma_f32 v[48:49], v[170:171], v[42:43], v[48:49] op_sel_hi:[1,0,1]
	v_fmac_f32_e32 v43, v186, v42
	v_pk_fma_f32 v[34:35], v[34:35], v[156:157], v[46:47]
	v_pk_fma_f32 v[36:37], v[36:37], v[158:159], v[48:49]
	v_pk_fma_f32 v[50:51], v[168:169], v[54:55], v[50:51] op_sel_hi:[1,0,1]
	v_pk_fma_f32 v[52:53], v[170:171], v[54:55], v[52:53] op_sel_hi:[1,0,1]
	v_fmac_f32_e32 v43, v177, v187
	v_pk_fma_f32 v[38:39], v[38:39], v[156:157], v[50:51]
	v_pk_fma_f32 v[40:41], v[40:41], v[158:159], v[52:53]
	v_cndmask_b32_e64 v55, v55, v43, s[50:51]
	ds_read_b128 v[152:155], v208 offset:1792
	ds_read_b128 v[156:159], v208 offset:17152
	ds_read_b128 v[168:171], v208 offset:25344
	ds_read_b128 v[172:175], v208 offset:33536
	ds_read_b128 v[192:195], v209 offset:40976
	ds_read_b128 v[196:199], v210 offset:40976
	ds_read_b128 v[200:203], v211 offset:49696
	ds_read_b128 v[204:207], v211 offset:49712
	s_waitcnt lgkmcnt(9)
	v_pk_mul_f32 v[42:43], v[34:35], v[128:129] op_sel_hi:[0,1]
	v_pk_mul_f32 v[44:45], v[38:39], v[128:129] op_sel_hi:[0,1]
	v_pk_fma_f32 v[42:43], v[34:35], v[130:131], v[42:43] op_sel:[1,0,0]
	v_pk_fma_f32 v[44:45], v[38:39], v[130:131], v[44:45] op_sel:[1,0,0]
	v_pk_fma_f32 v[42:43], v[36:37], v[132:133], v[42:43] op_sel_hi:[0,1,1]
	v_pk_fma_f32 v[44:45], v[40:41], v[132:133], v[44:45] op_sel_hi:[0,1,1]
	v_pk_fma_f32 v[42:43], v[36:37], v[134:135], v[42:43] op_sel:[1,0,0]
	v_pk_fma_f32 v[44:45], v[40:41], v[134:135], v[44:45] op_sel:[1,0,0]
	v_pk_mul_f32 v[46:47], v[144:145], v[178:179] op_sel_hi:[1,0]
	v_pk_mul_f32 v[48:49], v[146:147], v[178:179] op_sel_hi:[1,0]
	v_add_f32_dpp v42, v44, v42 quad_perm:[1,0,3,2] row_mask:0xf bank_mask:0xf bound_ctrl:1
	v_add_f32_dpp v43, v45, v43 quad_perm:[1,0,3,2] row_mask:0xf bank_mask:0xf bound_ctrl:1
	v_pk_mul_f32 v[50:51], v[144:145], v[182:183] op_sel_hi:[1,0]
	v_add_f32_dpp v42, v42, v42 quad_perm:[2,3,0,1] row_mask:0xf bank_mask:0xf bound_ctrl:1
	v_add_f32_dpp v43, v43, v43 quad_perm:[2,3,0,1] row_mask:0xf bank_mask:0xf bound_ctrl:1
	v_pk_mul_f32 v[52:53], v[146:147], v[182:183] op_sel_hi:[1,0]
	v_add_f32_dpp v42, v42, v42 row_ror:4 row_mask:0xf bank_mask:0xf bound_ctrl:1
	v_add_f32_dpp v43, v43, v43 row_ror:4 row_mask:0xf bank_mask:0xf bound_ctrl:1
	ds_read_b128 v[128:131], v208 offset:2048
	v_add_f32_dpp v42, v42, v42 row_ror:8 row_mask:0xf bank_mask:0xf bound_ctrl:1
	v_add_f32_dpp v43, v43, v43 row_ror:8 row_mask:0xf bank_mask:0xf bound_ctrl:1
	v_pk_fma_f32 v[46:47], v[140:141], v[42:43], v[46:47] op_sel_hi:[1,0,1]
	v_mov_b32_dpp v54, v42 quad_perm:[1,0,3,2] row_mask:0xf bank_mask:0xf bound_ctrl:1
	v_pk_fma_f32 v[48:49], v[142:143], v[42:43], v[48:49] op_sel_hi:[1,0,1]
	v_fmac_f32_e32 v43, v188, v42
	v_pk_fma_f32 v[34:35], v[34:35], v[136:137], v[46:47]
	v_pk_fma_f32 v[36:37], v[36:37], v[138:139], v[48:49]
	v_pk_fma_f32 v[50:51], v[140:141], v[54:55], v[50:51] op_sel_hi:[1,0,1]
	v_pk_fma_f32 v[52:53], v[142:143], v[54:55], v[52:53] op_sel_hi:[1,0,1]
	v_fmac_f32_e32 v43, v178, v189
	v_pk_fma_f32 v[38:39], v[38:39], v[136:137], v[50:51]
	v_pk_fma_f32 v[40:41], v[40:41], v[138:139], v[52:53]
	v_cndmask_b32_e64 v55, v55, v43, s[52:53]
	ds_read_b128 v[132:135], v208 offset:2304
	ds_read_b128 v[136:139], v208 offset:17408
	ds_read_b128 v[140:143], v208 offset:25600
	ds_read_b128 v[144:147], v208 offset:33792
	s_waitcnt lgkmcnt(9)
	v_pk_mul_f32 v[42:43], v[34:35], v[148:149] op_sel_hi:[0,1]
	v_pk_mul_f32 v[44:45], v[38:39], v[148:149] op_sel_hi:[0,1]
	v_pk_fma_f32 v[42:43], v[34:35], v[150:151], v[42:43] op_sel:[1,0,0]
	v_pk_fma_f32 v[44:45], v[38:39], v[150:151], v[44:45] op_sel:[1,0,0]
	v_pk_fma_f32 v[42:43], v[36:37], v[152:153], v[42:43] op_sel_hi:[0,1,1]
	v_pk_fma_f32 v[44:45], v[40:41], v[152:153], v[44:45] op_sel_hi:[0,1,1]
	v_pk_fma_f32 v[42:43], v[36:37], v[154:155], v[42:43] op_sel:[1,0,0]
	v_pk_fma_f32 v[44:45], v[40:41], v[154:155], v[44:45] op_sel:[1,0,0]
	v_pk_mul_f32 v[46:47], v[172:173], v[178:179] op_sel:[0,1]
	v_pk_mul_f32 v[48:49], v[174:175], v[178:179] op_sel:[0,1]
	v_add_f32_dpp v42, v44, v42 quad_perm:[1,0,3,2] row_mask:0xf bank_mask:0xf bound_ctrl:1
	v_add_f32_dpp v43, v45, v43 quad_perm:[1,0,3,2] row_mask:0xf bank_mask:0xf bound_ctrl:1
	v_pk_mul_f32 v[50:51], v[172:173], v[182:183] op_sel:[0,1]
	v_add_f32_dpp v42, v42, v42 quad_perm:[2,3,0,1] row_mask:0xf bank_mask:0xf bound_ctrl:1
	v_add_f32_dpp v43, v43, v43 quad_perm:[2,3,0,1] row_mask:0xf bank_mask:0xf bound_ctrl:1
	v_pk_mul_f32 v[52:53], v[174:175], v[182:183] op_sel:[0,1]
	v_add_f32_dpp v42, v42, v42 row_ror:4 row_mask:0xf bank_mask:0xf bound_ctrl:1
	v_add_f32_dpp v43, v43, v43 row_ror:4 row_mask:0xf bank_mask:0xf bound_ctrl:1
	ds_read_b128 v[148:151], v208 offset:2560
	v_add_f32_dpp v42, v42, v42 row_ror:8 row_mask:0xf bank_mask:0xf bound_ctrl:1
	v_add_f32_dpp v43, v43, v43 row_ror:8 row_mask:0xf bank_mask:0xf bound_ctrl:1
	v_pk_fma_f32 v[46:47], v[168:169], v[42:43], v[46:47] op_sel_hi:[1,0,1]
	v_mov_b32_dpp v54, v42 quad_perm:[1,0,3,2] row_mask:0xf bank_mask:0xf bound_ctrl:1
	v_pk_fma_f32 v[48:49], v[170:171], v[42:43], v[48:49] op_sel_hi:[1,0,1]
	v_fmac_f32_e32 v43, v190, v42
	v_pk_fma_f32 v[34:35], v[34:35], v[156:157], v[46:47]
	v_pk_fma_f32 v[36:37], v[36:37], v[158:159], v[48:49]
	v_pk_fma_f32 v[50:51], v[168:169], v[54:55], v[50:51] op_sel_hi:[1,0,1]
	v_pk_fma_f32 v[52:53], v[170:171], v[54:55], v[52:53] op_sel_hi:[1,0,1]
	v_fmac_f32_e32 v43, v179, v191
	v_pk_fma_f32 v[38:39], v[38:39], v[156:157], v[50:51]
	v_pk_fma_f32 v[40:41], v[40:41], v[158:159], v[52:53]
	v_cndmask_b32_e64 v55, v55, v43, s[54:55]
	ds_read_b128 v[152:155], v208 offset:2816
	ds_read_b128 v[156:159], v208 offset:17664
	ds_read_b128 v[168:171], v208 offset:25856
	ds_read_b128 v[172:175], v208 offset:34048
	s_waitcnt lgkmcnt(5)
	v_pk_mul_f32 v[42:43], v[34:35], v[128:129] op_sel_hi:[0,1]
	v_pk_mul_f32 v[44:45], v[38:39], v[128:129] op_sel_hi:[0,1]
	v_pk_fma_f32 v[42:43], v[34:35], v[130:131], v[42:43] op_sel:[1,0,0]
	v_pk_fma_f32 v[44:45], v[38:39], v[130:131], v[44:45] op_sel:[1,0,0]
	v_pk_fma_f32 v[42:43], v[36:37], v[132:133], v[42:43] op_sel_hi:[0,1,1]
	v_pk_fma_f32 v[44:45], v[40:41], v[132:133], v[44:45] op_sel_hi:[0,1,1]
	v_pk_fma_f32 v[42:43], v[36:37], v[134:135], v[42:43] op_sel:[1,0,0]
	v_pk_fma_f32 v[44:45], v[40:41], v[134:135], v[44:45] op_sel:[1,0,0]
	v_pk_mul_f32 v[46:47], v[144:145], v[192:193] op_sel_hi:[1,0]
	v_pk_mul_f32 v[48:49], v[146:147], v[192:193] op_sel_hi:[1,0]
	v_add_f32_dpp v42, v44, v42 quad_perm:[1,0,3,2] row_mask:0xf bank_mask:0xf bound_ctrl:1
	v_add_f32_dpp v43, v45, v43 quad_perm:[1,0,3,2] row_mask:0xf bank_mask:0xf bound_ctrl:1
	v_pk_mul_f32 v[50:51], v[144:145], v[196:197] op_sel_hi:[1,0]
	v_add_f32_dpp v42, v42, v42 quad_perm:[2,3,0,1] row_mask:0xf bank_mask:0xf bound_ctrl:1
	v_add_f32_dpp v43, v43, v43 quad_perm:[2,3,0,1] row_mask:0xf bank_mask:0xf bound_ctrl:1
	v_pk_mul_f32 v[52:53], v[146:147], v[196:197] op_sel_hi:[1,0]
	v_add_f32_dpp v42, v42, v42 row_ror:4 row_mask:0xf bank_mask:0xf bound_ctrl:1
	v_add_f32_dpp v43, v43, v43 row_ror:4 row_mask:0xf bank_mask:0xf bound_ctrl:1
	ds_read_b128 v[128:131], v208 offset:3072
	v_add_f32_dpp v42, v42, v42 row_ror:8 row_mask:0xf bank_mask:0xf bound_ctrl:1
	v_add_f32_dpp v43, v43, v43 row_ror:8 row_mask:0xf bank_mask:0xf bound_ctrl:1
	v_pk_fma_f32 v[46:47], v[140:141], v[42:43], v[46:47] op_sel_hi:[1,0,1]
	v_mov_b32_dpp v54, v42 quad_perm:[1,0,3,2] row_mask:0xf bank_mask:0xf bound_ctrl:1
	v_pk_fma_f32 v[48:49], v[142:143], v[42:43], v[48:49] op_sel_hi:[1,0,1]
	v_fmac_f32_e32 v43, v200, v42
	v_pk_fma_f32 v[34:35], v[34:35], v[136:137], v[46:47]
	v_pk_fma_f32 v[36:37], v[36:37], v[138:139], v[48:49]
	v_pk_fma_f32 v[50:51], v[140:141], v[54:55], v[50:51] op_sel_hi:[1,0,1]
	v_pk_fma_f32 v[52:53], v[142:143], v[54:55], v[52:53] op_sel_hi:[1,0,1]
	v_fmac_f32_e32 v43, v192, v201
	v_pk_fma_f32 v[38:39], v[38:39], v[136:137], v[50:51]
	v_pk_fma_f32 v[40:41], v[40:41], v[138:139], v[52:53]
	v_cndmask_b32_e64 v55, v55, v43, s[56:57]
	ds_read_b128 v[132:135], v208 offset:3328
	ds_read_b128 v[136:139], v208 offset:17920
	ds_read_b128 v[140:143], v208 offset:26112
	ds_read_b128 v[144:147], v208 offset:34304
	s_waitcnt lgkmcnt(5)
	v_pk_mul_f32 v[42:43], v[34:35], v[148:149] op_sel_hi:[0,1]
	v_pk_mul_f32 v[44:45], v[38:39], v[148:149] op_sel_hi:[0,1]
	v_pk_fma_f32 v[42:43], v[34:35], v[150:151], v[42:43] op_sel:[1,0,0]
	v_pk_fma_f32 v[44:45], v[38:39], v[150:151], v[44:45] op_sel:[1,0,0]
	v_pk_fma_f32 v[42:43], v[36:37], v[152:153], v[42:43] op_sel_hi:[0,1,1]
	v_pk_fma_f32 v[44:45], v[40:41], v[152:153], v[44:45] op_sel_hi:[0,1,1]
	v_pk_fma_f32 v[42:43], v[36:37], v[154:155], v[42:43] op_sel:[1,0,0]
	v_pk_fma_f32 v[44:45], v[40:41], v[154:155], v[44:45] op_sel:[1,0,0]
	v_pk_mul_f32 v[46:47], v[172:173], v[192:193] op_sel:[0,1]
	v_pk_mul_f32 v[48:49], v[174:175], v[192:193] op_sel:[0,1]
	v_add_f32_dpp v42, v44, v42 quad_perm:[1,0,3,2] row_mask:0xf bank_mask:0xf bound_ctrl:1
	v_add_f32_dpp v43, v45, v43 quad_perm:[1,0,3,2] row_mask:0xf bank_mask:0xf bound_ctrl:1
	v_pk_mul_f32 v[50:51], v[172:173], v[196:197] op_sel:[0,1]
	v_add_f32_dpp v42, v42, v42 quad_perm:[2,3,0,1] row_mask:0xf bank_mask:0xf bound_ctrl:1
	v_add_f32_dpp v43, v43, v43 quad_perm:[2,3,0,1] row_mask:0xf bank_mask:0xf bound_ctrl:1
	v_pk_mul_f32 v[52:53], v[174:175], v[196:197] op_sel:[0,1]
	v_add_f32_dpp v42, v42, v42 row_ror:4 row_mask:0xf bank_mask:0xf bound_ctrl:1
	v_add_f32_dpp v43, v43, v43 row_ror:4 row_mask:0xf bank_mask:0xf bound_ctrl:1
	ds_read_b128 v[148:151], v208 offset:3584
	v_add_f32_dpp v42, v42, v42 row_ror:8 row_mask:0xf bank_mask:0xf bound_ctrl:1
	v_add_f32_dpp v43, v43, v43 row_ror:8 row_mask:0xf bank_mask:0xf bound_ctrl:1
	v_pk_fma_f32 v[46:47], v[168:169], v[42:43], v[46:47] op_sel_hi:[1,0,1]
	v_mov_b32_dpp v54, v42 quad_perm:[1,0,3,2] row_mask:0xf bank_mask:0xf bound_ctrl:1
	v_pk_fma_f32 v[48:49], v[170:171], v[42:43], v[48:49] op_sel_hi:[1,0,1]
	v_fmac_f32_e32 v43, v202, v42
	v_pk_fma_f32 v[34:35], v[34:35], v[156:157], v[46:47]
	v_pk_fma_f32 v[36:37], v[36:37], v[158:159], v[48:49]
	v_pk_fma_f32 v[50:51], v[168:169], v[54:55], v[50:51] op_sel_hi:[1,0,1]
	v_pk_fma_f32 v[52:53], v[170:171], v[54:55], v[52:53] op_sel_hi:[1,0,1]
	v_fmac_f32_e32 v43, v193, v203
	v_pk_fma_f32 v[38:39], v[38:39], v[156:157], v[50:51]
	v_pk_fma_f32 v[40:41], v[40:41], v[158:159], v[52:53]
	v_cndmask_b32_e64 v55, v55, v43, s[58:59]
	ds_read_b128 v[152:155], v208 offset:3840
	ds_read_b128 v[156:159], v208 offset:18176
	ds_read_b128 v[168:171], v208 offset:26368
	ds_read_b128 v[172:175], v208 offset:34560
	ds_read_b128 v[176:179], v209 offset:40992
	ds_read_b128 v[180:183], v210 offset:40992
	ds_read_b128 v[184:187], v211 offset:49728
	ds_read_b128 v[188:191], v211 offset:49744
	s_waitcnt lgkmcnt(9)
	v_pk_mul_f32 v[42:43], v[34:35], v[128:129] op_sel_hi:[0,1]
	v_pk_mul_f32 v[44:45], v[38:39], v[128:129] op_sel_hi:[0,1]
	v_pk_fma_f32 v[42:43], v[34:35], v[130:131], v[42:43] op_sel:[1,0,0]
	v_pk_fma_f32 v[44:45], v[38:39], v[130:131], v[44:45] op_sel:[1,0,0]
	v_pk_fma_f32 v[42:43], v[36:37], v[132:133], v[42:43] op_sel_hi:[0,1,1]
	v_pk_fma_f32 v[44:45], v[40:41], v[132:133], v[44:45] op_sel_hi:[0,1,1]
	v_pk_fma_f32 v[42:43], v[36:37], v[134:135], v[42:43] op_sel:[1,0,0]
	v_pk_fma_f32 v[44:45], v[40:41], v[134:135], v[44:45] op_sel:[1,0,0]
	v_pk_mul_f32 v[46:47], v[144:145], v[194:195] op_sel_hi:[1,0]
	v_pk_mul_f32 v[48:49], v[146:147], v[194:195] op_sel_hi:[1,0]
	v_add_f32_dpp v42, v44, v42 quad_perm:[1,0,3,2] row_mask:0xf bank_mask:0xf bound_ctrl:1
	v_add_f32_dpp v43, v45, v43 quad_perm:[1,0,3,2] row_mask:0xf bank_mask:0xf bound_ctrl:1
	v_pk_mul_f32 v[50:51], v[144:145], v[198:199] op_sel_hi:[1,0]
	v_add_f32_dpp v42, v42, v42 quad_perm:[2,3,0,1] row_mask:0xf bank_mask:0xf bound_ctrl:1
	v_add_f32_dpp v43, v43, v43 quad_perm:[2,3,0,1] row_mask:0xf bank_mask:0xf bound_ctrl:1
	v_pk_mul_f32 v[52:53], v[146:147], v[198:199] op_sel_hi:[1,0]
	v_add_f32_dpp v42, v42, v42 row_ror:4 row_mask:0xf bank_mask:0xf bound_ctrl:1
	v_add_f32_dpp v43, v43, v43 row_ror:4 row_mask:0xf bank_mask:0xf bound_ctrl:1
	ds_read_b128 v[128:131], v208 offset:4096
	v_add_f32_dpp v42, v42, v42 row_ror:8 row_mask:0xf bank_mask:0xf bound_ctrl:1
	v_add_f32_dpp v43, v43, v43 row_ror:8 row_mask:0xf bank_mask:0xf bound_ctrl:1
	v_pk_fma_f32 v[46:47], v[140:141], v[42:43], v[46:47] op_sel_hi:[1,0,1]
	v_mov_b32_dpp v54, v42 quad_perm:[1,0,3,2] row_mask:0xf bank_mask:0xf bound_ctrl:1
	v_pk_fma_f32 v[48:49], v[142:143], v[42:43], v[48:49] op_sel_hi:[1,0,1]
	v_fmac_f32_e32 v43, v204, v42
	v_pk_fma_f32 v[34:35], v[34:35], v[136:137], v[46:47]
	v_pk_fma_f32 v[36:37], v[36:37], v[138:139], v[48:49]
	v_pk_fma_f32 v[50:51], v[140:141], v[54:55], v[50:51] op_sel_hi:[1,0,1]
	v_pk_fma_f32 v[52:53], v[142:143], v[54:55], v[52:53] op_sel_hi:[1,0,1]
	v_fmac_f32_e32 v43, v194, v205
	v_pk_fma_f32 v[38:39], v[38:39], v[136:137], v[50:51]
	v_pk_fma_f32 v[40:41], v[40:41], v[138:139], v[52:53]
	v_cndmask_b32_e64 v55, v55, v43, s[60:61]
	ds_read_b128 v[132:135], v208 offset:4352
	ds_read_b128 v[136:139], v208 offset:18432
	ds_read_b128 v[140:143], v208 offset:26624
	ds_read_b128 v[144:147], v208 offset:34816
	s_waitcnt lgkmcnt(9)
	v_pk_mul_f32 v[42:43], v[34:35], v[148:149] op_sel_hi:[0,1]
	v_pk_mul_f32 v[44:45], v[38:39], v[148:149] op_sel_hi:[0,1]
	v_pk_fma_f32 v[42:43], v[34:35], v[150:151], v[42:43] op_sel:[1,0,0]
	v_pk_fma_f32 v[44:45], v[38:39], v[150:151], v[44:45] op_sel:[1,0,0]
	v_pk_fma_f32 v[42:43], v[36:37], v[152:153], v[42:43] op_sel_hi:[0,1,1]
	v_pk_fma_f32 v[44:45], v[40:41], v[152:153], v[44:45] op_sel_hi:[0,1,1]
	v_pk_fma_f32 v[42:43], v[36:37], v[154:155], v[42:43] op_sel:[1,0,0]
	v_pk_fma_f32 v[44:45], v[40:41], v[154:155], v[44:45] op_sel:[1,0,0]
	v_pk_mul_f32 v[46:47], v[172:173], v[194:195] op_sel:[0,1]
	v_pk_mul_f32 v[48:49], v[174:175], v[194:195] op_sel:[0,1]
	v_add_f32_dpp v42, v44, v42 quad_perm:[1,0,3,2] row_mask:0xf bank_mask:0xf bound_ctrl:1
	v_add_f32_dpp v43, v45, v43 quad_perm:[1,0,3,2] row_mask:0xf bank_mask:0xf bound_ctrl:1
	v_pk_mul_f32 v[50:51], v[172:173], v[198:199] op_sel:[0,1]
	v_add_f32_dpp v42, v42, v42 quad_perm:[2,3,0,1] row_mask:0xf bank_mask:0xf bound_ctrl:1
	v_add_f32_dpp v43, v43, v43 quad_perm:[2,3,0,1] row_mask:0xf bank_mask:0xf bound_ctrl:1
	v_pk_mul_f32 v[52:53], v[174:175], v[198:199] op_sel:[0,1]
	v_add_f32_dpp v42, v42, v42 row_ror:4 row_mask:0xf bank_mask:0xf bound_ctrl:1
	v_add_f32_dpp v43, v43, v43 row_ror:4 row_mask:0xf bank_mask:0xf bound_ctrl:1
	ds_read_b128 v[148:151], v208 offset:4608
	v_add_f32_dpp v42, v42, v42 row_ror:8 row_mask:0xf bank_mask:0xf bound_ctrl:1
	v_add_f32_dpp v43, v43, v43 row_ror:8 row_mask:0xf bank_mask:0xf bound_ctrl:1
	v_pk_fma_f32 v[46:47], v[168:169], v[42:43], v[46:47] op_sel_hi:[1,0,1]
	v_mov_b32_dpp v54, v42 quad_perm:[1,0,3,2] row_mask:0xf bank_mask:0xf bound_ctrl:1
	v_pk_fma_f32 v[48:49], v[170:171], v[42:43], v[48:49] op_sel_hi:[1,0,1]
	v_fmac_f32_e32 v43, v206, v42
	v_pk_fma_f32 v[34:35], v[34:35], v[156:157], v[46:47]
	v_pk_fma_f32 v[36:37], v[36:37], v[158:159], v[48:49]
	v_pk_fma_f32 v[50:51], v[168:169], v[54:55], v[50:51] op_sel_hi:[1,0,1]
	v_pk_fma_f32 v[52:53], v[170:171], v[54:55], v[52:53] op_sel_hi:[1,0,1]
	v_fmac_f32_e32 v43, v195, v207
	v_pk_fma_f32 v[38:39], v[38:39], v[156:157], v[50:51]
	v_pk_fma_f32 v[40:41], v[40:41], v[158:159], v[52:53]
	v_cndmask_b32_e64 v55, v55, v43, s[62:63]
	ds_write_b32 v212, v55 offset:0
	ds_read_b128 v[152:155], v208 offset:4864
	ds_read_b128 v[156:159], v208 offset:18688
	ds_read_b128 v[168:171], v208 offset:26880
	ds_read_b128 v[172:175], v208 offset:35072
	s_waitcnt lgkmcnt(6)
	v_pk_mul_f32 v[42:43], v[34:35], v[128:129] op_sel_hi:[0,1]
	v_pk_mul_f32 v[44:45], v[38:39], v[128:129] op_sel_hi:[0,1]
	v_pk_fma_f32 v[42:43], v[34:35], v[130:131], v[42:43] op_sel:[1,0,0]
	v_pk_fma_f32 v[44:45], v[38:39], v[130:131], v[44:45] op_sel:[1,0,0]
	v_pk_fma_f32 v[42:43], v[36:37], v[132:133], v[42:43] op_sel_hi:[0,1,1]
	v_pk_fma_f32 v[44:45], v[40:41], v[132:133], v[44:45] op_sel_hi:[0,1,1]
	v_pk_fma_f32 v[42:43], v[36:37], v[134:135], v[42:43] op_sel:[1,0,0]
	v_pk_fma_f32 v[44:45], v[40:41], v[134:135], v[44:45] op_sel:[1,0,0]
	v_pk_mul_f32 v[46:47], v[144:145], v[176:177] op_sel_hi:[1,0]
	v_pk_mul_f32 v[48:49], v[146:147], v[176:177] op_sel_hi:[1,0]
	v_add_f32_dpp v42, v44, v42 quad_perm:[1,0,3,2] row_mask:0xf bank_mask:0xf bound_ctrl:1
	v_add_f32_dpp v43, v45, v43 quad_perm:[1,0,3,2] row_mask:0xf bank_mask:0xf bound_ctrl:1
	v_pk_mul_f32 v[50:51], v[144:145], v[180:181] op_sel_hi:[1,0]
	v_add_f32_dpp v42, v42, v42 quad_perm:[2,3,0,1] row_mask:0xf bank_mask:0xf bound_ctrl:1
	v_add_f32_dpp v43, v43, v43 quad_perm:[2,3,0,1] row_mask:0xf bank_mask:0xf bound_ctrl:1
	v_pk_mul_f32 v[52:53], v[146:147], v[180:181] op_sel_hi:[1,0]
	v_add_f32_dpp v42, v42, v42 row_ror:4 row_mask:0xf bank_mask:0xf bound_ctrl:1
	v_add_f32_dpp v43, v43, v43 row_ror:4 row_mask:0xf bank_mask:0xf bound_ctrl:1
	ds_read_b128 v[128:131], v208 offset:5120
	v_add_f32_dpp v42, v42, v42 row_ror:8 row_mask:0xf bank_mask:0xf bound_ctrl:1
	v_add_f32_dpp v43, v43, v43 row_ror:8 row_mask:0xf bank_mask:0xf bound_ctrl:1
	v_pk_fma_f32 v[46:47], v[140:141], v[42:43], v[46:47] op_sel_hi:[1,0,1]
	v_mov_b32_dpp v54, v42 quad_perm:[1,0,3,2] row_mask:0xf bank_mask:0xf bound_ctrl:1
	v_pk_fma_f32 v[48:49], v[142:143], v[42:43], v[48:49] op_sel_hi:[1,0,1]
	v_fmac_f32_e32 v43, v184, v42
	v_pk_fma_f32 v[34:35], v[34:35], v[136:137], v[46:47]
	v_pk_fma_f32 v[36:37], v[36:37], v[138:139], v[48:49]
	v_pk_fma_f32 v[50:51], v[140:141], v[54:55], v[50:51] op_sel_hi:[1,0,1]
	v_pk_fma_f32 v[52:53], v[142:143], v[54:55], v[52:53] op_sel_hi:[1,0,1]
	v_fmac_f32_e32 v43, v176, v185
	v_pk_fma_f32 v[38:39], v[38:39], v[136:137], v[50:51]
	v_pk_fma_f32 v[40:41], v[40:41], v[138:139], v[52:53]
	v_cndmask_b32_e64 v55, 0, v43, s[48:49]
	ds_read_b128 v[132:135], v208 offset:5376
	ds_read_b128 v[136:139], v208 offset:18944
	ds_read_b128 v[140:143], v208 offset:27136
	ds_read_b128 v[144:147], v208 offset:35328
	s_waitcnt lgkmcnt(5)
	v_pk_mul_f32 v[42:43], v[34:35], v[148:149] op_sel_hi:[0,1]
	v_pk_mul_f32 v[44:45], v[38:39], v[148:149] op_sel_hi:[0,1]
	v_pk_fma_f32 v[42:43], v[34:35], v[150:151], v[42:43] op_sel:[1,0,0]
	v_pk_fma_f32 v[44:45], v[38:39], v[150:151], v[44:45] op_sel:[1,0,0]
	v_pk_fma_f32 v[42:43], v[36:37], v[152:153], v[42:43] op_sel_hi:[0,1,1]
	v_pk_fma_f32 v[44:45], v[40:41], v[152:153], v[44:45] op_sel_hi:[0,1,1]
	v_pk_fma_f32 v[42:43], v[36:37], v[154:155], v[42:43] op_sel:[1,0,0]
	v_pk_fma_f32 v[44:45], v[40:41], v[154:155], v[44:45] op_sel:[1,0,0]
	v_pk_mul_f32 v[46:47], v[172:173], v[176:177] op_sel:[0,1]
	v_pk_mul_f32 v[48:49], v[174:175], v[176:177] op_sel:[0,1]
	v_add_f32_dpp v42, v44, v42 quad_perm:[1,0,3,2] row_mask:0xf bank_mask:0xf bound_ctrl:1
	v_add_f32_dpp v43, v45, v43 quad_perm:[1,0,3,2] row_mask:0xf bank_mask:0xf bound_ctrl:1
	v_pk_mul_f32 v[50:51], v[172:173], v[180:181] op_sel:[0,1]
	v_add_f32_dpp v42, v42, v42 quad_perm:[2,3,0,1] row_mask:0xf bank_mask:0xf bound_ctrl:1
	v_add_f32_dpp v43, v43, v43 quad_perm:[2,3,0,1] row_mask:0xf bank_mask:0xf bound_ctrl:1
	v_pk_mul_f32 v[52:53], v[174:175], v[180:181] op_sel:[0,1]
	v_add_f32_dpp v42, v42, v42 row_ror:4 row_mask:0xf bank_mask:0xf bound_ctrl:1
	v_add_f32_dpp v43, v43, v43 row_ror:4 row_mask:0xf bank_mask:0xf bound_ctrl:1
	ds_read_b128 v[148:151], v208 offset:5632
	v_add_f32_dpp v42, v42, v42 row_ror:8 row_mask:0xf bank_mask:0xf bound_ctrl:1
	v_add_f32_dpp v43, v43, v43 row_ror:8 row_mask:0xf bank_mask:0xf bound_ctrl:1
	v_pk_fma_f32 v[46:47], v[168:169], v[42:43], v[46:47] op_sel_hi:[1,0,1]
	v_mov_b32_dpp v54, v42 quad_perm:[1,0,3,2] row_mask:0xf bank_mask:0xf bound_ctrl:1
	v_pk_fma_f32 v[48:49], v[170:171], v[42:43], v[48:49] op_sel_hi:[1,0,1]
	v_fmac_f32_e32 v43, v186, v42
	v_pk_fma_f32 v[34:35], v[34:35], v[156:157], v[46:47]
	v_pk_fma_f32 v[36:37], v[36:37], v[158:159], v[48:49]
	v_pk_fma_f32 v[50:51], v[168:169], v[54:55], v[50:51] op_sel_hi:[1,0,1]
	v_pk_fma_f32 v[52:53], v[170:171], v[54:55], v[52:53] op_sel_hi:[1,0,1]
	v_fmac_f32_e32 v43, v177, v187
	v_pk_fma_f32 v[38:39], v[38:39], v[156:157], v[50:51]
	v_pk_fma_f32 v[40:41], v[40:41], v[158:159], v[52:53]
	v_cndmask_b32_e64 v55, v55, v43, s[50:51]
	ds_read_b128 v[152:155], v208 offset:5888
	ds_read_b128 v[156:159], v208 offset:19200
	ds_read_b128 v[168:171], v208 offset:27392
	ds_read_b128 v[172:175], v208 offset:35584
	ds_read_b128 v[192:195], v209 offset:41008
	ds_read_b128 v[196:199], v210 offset:41008
	ds_read_b128 v[200:203], v211 offset:49760
	ds_read_b128 v[204:207], v211 offset:49776
	s_waitcnt lgkmcnt(9)
	v_pk_mul_f32 v[42:43], v[34:35], v[128:129] op_sel_hi:[0,1]
	v_pk_mul_f32 v[44:45], v[38:39], v[128:129] op_sel_hi:[0,1]
	v_pk_fma_f32 v[42:43], v[34:35], v[130:131], v[42:43] op_sel:[1,0,0]
	v_pk_fma_f32 v[44:45], v[38:39], v[130:131], v[44:45] op_sel:[1,0,0]
	v_pk_fma_f32 v[42:43], v[36:37], v[132:133], v[42:43] op_sel_hi:[0,1,1]
	v_pk_fma_f32 v[44:45], v[40:41], v[132:133], v[44:45] op_sel_hi:[0,1,1]
	v_pk_fma_f32 v[42:43], v[36:37], v[134:135], v[42:43] op_sel:[1,0,0]
	v_pk_fma_f32 v[44:45], v[40:41], v[134:135], v[44:45] op_sel:[1,0,0]
	v_pk_mul_f32 v[46:47], v[144:145], v[178:179] op_sel_hi:[1,0]
	v_pk_mul_f32 v[48:49], v[146:147], v[178:179] op_sel_hi:[1,0]
	v_add_f32_dpp v42, v44, v42 quad_perm:[1,0,3,2] row_mask:0xf bank_mask:0xf bound_ctrl:1
	v_add_f32_dpp v43, v45, v43 quad_perm:[1,0,3,2] row_mask:0xf bank_mask:0xf bound_ctrl:1
	v_pk_mul_f32 v[50:51], v[144:145], v[182:183] op_sel_hi:[1,0]
	v_add_f32_dpp v42, v42, v42 quad_perm:[2,3,0,1] row_mask:0xf bank_mask:0xf bound_ctrl:1
	v_add_f32_dpp v43, v43, v43 quad_perm:[2,3,0,1] row_mask:0xf bank_mask:0xf bound_ctrl:1
	v_pk_mul_f32 v[52:53], v[146:147], v[182:183] op_sel_hi:[1,0]
	v_add_f32_dpp v42, v42, v42 row_ror:4 row_mask:0xf bank_mask:0xf bound_ctrl:1
	v_add_f32_dpp v43, v43, v43 row_ror:4 row_mask:0xf bank_mask:0xf bound_ctrl:1
	ds_read_b128 v[128:131], v208 offset:6144
	v_add_f32_dpp v42, v42, v42 row_ror:8 row_mask:0xf bank_mask:0xf bound_ctrl:1
	v_add_f32_dpp v43, v43, v43 row_ror:8 row_mask:0xf bank_mask:0xf bound_ctrl:1
	v_pk_fma_f32 v[46:47], v[140:141], v[42:43], v[46:47] op_sel_hi:[1,0,1]
	v_mov_b32_dpp v54, v42 quad_perm:[1,0,3,2] row_mask:0xf bank_mask:0xf bound_ctrl:1
	v_pk_fma_f32 v[48:49], v[142:143], v[42:43], v[48:49] op_sel_hi:[1,0,1]
	v_fmac_f32_e32 v43, v188, v42
	v_pk_fma_f32 v[34:35], v[34:35], v[136:137], v[46:47]
	v_pk_fma_f32 v[36:37], v[36:37], v[138:139], v[48:49]
	v_pk_fma_f32 v[50:51], v[140:141], v[54:55], v[50:51] op_sel_hi:[1,0,1]
	v_pk_fma_f32 v[52:53], v[142:143], v[54:55], v[52:53] op_sel_hi:[1,0,1]
	v_fmac_f32_e32 v43, v178, v189
	v_pk_fma_f32 v[38:39], v[38:39], v[136:137], v[50:51]
	v_pk_fma_f32 v[40:41], v[40:41], v[138:139], v[52:53]
	v_cndmask_b32_e64 v55, v55, v43, s[52:53]
	ds_read_b128 v[132:135], v208 offset:6400
	ds_read_b128 v[136:139], v208 offset:19456
	ds_read_b128 v[140:143], v208 offset:27648
	ds_read_b128 v[144:147], v208 offset:35840
	s_waitcnt lgkmcnt(9)
	v_pk_mul_f32 v[42:43], v[34:35], v[148:149] op_sel_hi:[0,1]
	v_pk_mul_f32 v[44:45], v[38:39], v[148:149] op_sel_hi:[0,1]
	v_pk_fma_f32 v[42:43], v[34:35], v[150:151], v[42:43] op_sel:[1,0,0]
	v_pk_fma_f32 v[44:45], v[38:39], v[150:151], v[44:45] op_sel:[1,0,0]
	v_pk_fma_f32 v[42:43], v[36:37], v[152:153], v[42:43] op_sel_hi:[0,1,1]
	v_pk_fma_f32 v[44:45], v[40:41], v[152:153], v[44:45] op_sel_hi:[0,1,1]
	v_pk_fma_f32 v[42:43], v[36:37], v[154:155], v[42:43] op_sel:[1,0,0]
	v_pk_fma_f32 v[44:45], v[40:41], v[154:155], v[44:45] op_sel:[1,0,0]
	v_pk_mul_f32 v[46:47], v[172:173], v[178:179] op_sel:[0,1]
	v_pk_mul_f32 v[48:49], v[174:175], v[178:179] op_sel:[0,1]
	v_add_f32_dpp v42, v44, v42 quad_perm:[1,0,3,2] row_mask:0xf bank_mask:0xf bound_ctrl:1
	v_add_f32_dpp v43, v45, v43 quad_perm:[1,0,3,2] row_mask:0xf bank_mask:0xf bound_ctrl:1
	v_pk_mul_f32 v[50:51], v[172:173], v[182:183] op_sel:[0,1]
	v_add_f32_dpp v42, v42, v42 quad_perm:[2,3,0,1] row_mask:0xf bank_mask:0xf bound_ctrl:1
	v_add_f32_dpp v43, v43, v43 quad_perm:[2,3,0,1] row_mask:0xf bank_mask:0xf bound_ctrl:1
	v_pk_mul_f32 v[52:53], v[174:175], v[182:183] op_sel:[0,1]
	v_add_f32_dpp v42, v42, v42 row_ror:4 row_mask:0xf bank_mask:0xf bound_ctrl:1
	v_add_f32_dpp v43, v43, v43 row_ror:4 row_mask:0xf bank_mask:0xf bound_ctrl:1
	ds_read_b128 v[148:151], v208 offset:6656
	v_add_f32_dpp v42, v42, v42 row_ror:8 row_mask:0xf bank_mask:0xf bound_ctrl:1
	v_add_f32_dpp v43, v43, v43 row_ror:8 row_mask:0xf bank_mask:0xf bound_ctrl:1
	v_pk_fma_f32 v[46:47], v[168:169], v[42:43], v[46:47] op_sel_hi:[1,0,1]
	v_mov_b32_dpp v54, v42 quad_perm:[1,0,3,2] row_mask:0xf bank_mask:0xf bound_ctrl:1
	v_pk_fma_f32 v[48:49], v[170:171], v[42:43], v[48:49] op_sel_hi:[1,0,1]
	v_fmac_f32_e32 v43, v190, v42
	v_pk_fma_f32 v[34:35], v[34:35], v[156:157], v[46:47]
	v_pk_fma_f32 v[36:37], v[36:37], v[158:159], v[48:49]
	v_pk_fma_f32 v[50:51], v[168:169], v[54:55], v[50:51] op_sel_hi:[1,0,1]
	v_pk_fma_f32 v[52:53], v[170:171], v[54:55], v[52:53] op_sel_hi:[1,0,1]
	v_fmac_f32_e32 v43, v179, v191
	v_pk_fma_f32 v[38:39], v[38:39], v[156:157], v[50:51]
	v_pk_fma_f32 v[40:41], v[40:41], v[158:159], v[52:53]
	v_cndmask_b32_e64 v55, v55, v43, s[54:55]
	ds_read_b128 v[152:155], v208 offset:6912
	ds_read_b128 v[156:159], v208 offset:19712
	ds_read_b128 v[168:171], v208 offset:27904
	ds_read_b128 v[172:175], v208 offset:36096
	s_waitcnt lgkmcnt(5)
	v_pk_mul_f32 v[42:43], v[34:35], v[128:129] op_sel_hi:[0,1]
	v_pk_mul_f32 v[44:45], v[38:39], v[128:129] op_sel_hi:[0,1]
	v_pk_fma_f32 v[42:43], v[34:35], v[130:131], v[42:43] op_sel:[1,0,0]
	v_pk_fma_f32 v[44:45], v[38:39], v[130:131], v[44:45] op_sel:[1,0,0]
	v_pk_fma_f32 v[42:43], v[36:37], v[132:133], v[42:43] op_sel_hi:[0,1,1]
	v_pk_fma_f32 v[44:45], v[40:41], v[132:133], v[44:45] op_sel_hi:[0,1,1]
	v_pk_fma_f32 v[42:43], v[36:37], v[134:135], v[42:43] op_sel:[1,0,0]
	v_pk_fma_f32 v[44:45], v[40:41], v[134:135], v[44:45] op_sel:[1,0,0]
	v_pk_mul_f32 v[46:47], v[144:145], v[192:193] op_sel_hi:[1,0]
	v_pk_mul_f32 v[48:49], v[146:147], v[192:193] op_sel_hi:[1,0]
	v_add_f32_dpp v42, v44, v42 quad_perm:[1,0,3,2] row_mask:0xf bank_mask:0xf bound_ctrl:1
	v_add_f32_dpp v43, v45, v43 quad_perm:[1,0,3,2] row_mask:0xf bank_mask:0xf bound_ctrl:1
	v_pk_mul_f32 v[50:51], v[144:145], v[196:197] op_sel_hi:[1,0]
	v_add_f32_dpp v42, v42, v42 quad_perm:[2,3,0,1] row_mask:0xf bank_mask:0xf bound_ctrl:1
	v_add_f32_dpp v43, v43, v43 quad_perm:[2,3,0,1] row_mask:0xf bank_mask:0xf bound_ctrl:1
	v_pk_mul_f32 v[52:53], v[146:147], v[196:197] op_sel_hi:[1,0]
	v_add_f32_dpp v42, v42, v42 row_ror:4 row_mask:0xf bank_mask:0xf bound_ctrl:1
	v_add_f32_dpp v43, v43, v43 row_ror:4 row_mask:0xf bank_mask:0xf bound_ctrl:1
	ds_read_b128 v[128:131], v208 offset:7168
	v_add_f32_dpp v42, v42, v42 row_ror:8 row_mask:0xf bank_mask:0xf bound_ctrl:1
	v_add_f32_dpp v43, v43, v43 row_ror:8 row_mask:0xf bank_mask:0xf bound_ctrl:1
	v_pk_fma_f32 v[46:47], v[140:141], v[42:43], v[46:47] op_sel_hi:[1,0,1]
	v_mov_b32_dpp v54, v42 quad_perm:[1,0,3,2] row_mask:0xf bank_mask:0xf bound_ctrl:1
	v_pk_fma_f32 v[48:49], v[142:143], v[42:43], v[48:49] op_sel_hi:[1,0,1]
	v_fmac_f32_e32 v43, v200, v42
	v_pk_fma_f32 v[34:35], v[34:35], v[136:137], v[46:47]
	v_pk_fma_f32 v[36:37], v[36:37], v[138:139], v[48:49]
	v_pk_fma_f32 v[50:51], v[140:141], v[54:55], v[50:51] op_sel_hi:[1,0,1]
	v_pk_fma_f32 v[52:53], v[142:143], v[54:55], v[52:53] op_sel_hi:[1,0,1]
	v_fmac_f32_e32 v43, v192, v201
	v_pk_fma_f32 v[38:39], v[38:39], v[136:137], v[50:51]
	v_pk_fma_f32 v[40:41], v[40:41], v[138:139], v[52:53]
	v_cndmask_b32_e64 v55, v55, v43, s[56:57]
	ds_read_b128 v[132:135], v208 offset:7424
	ds_read_b128 v[136:139], v208 offset:19968
	ds_read_b128 v[140:143], v208 offset:28160
	ds_read_b128 v[144:147], v208 offset:36352
	s_waitcnt lgkmcnt(5)
	v_pk_mul_f32 v[42:43], v[34:35], v[148:149] op_sel_hi:[0,1]
	v_pk_mul_f32 v[44:45], v[38:39], v[148:149] op_sel_hi:[0,1]
	v_pk_fma_f32 v[42:43], v[34:35], v[150:151], v[42:43] op_sel:[1,0,0]
	v_pk_fma_f32 v[44:45], v[38:39], v[150:151], v[44:45] op_sel:[1,0,0]
	v_pk_fma_f32 v[42:43], v[36:37], v[152:153], v[42:43] op_sel_hi:[0,1,1]
	v_pk_fma_f32 v[44:45], v[40:41], v[152:153], v[44:45] op_sel_hi:[0,1,1]
	v_pk_fma_f32 v[42:43], v[36:37], v[154:155], v[42:43] op_sel:[1,0,0]
	v_pk_fma_f32 v[44:45], v[40:41], v[154:155], v[44:45] op_sel:[1,0,0]
	v_pk_mul_f32 v[46:47], v[172:173], v[192:193] op_sel:[0,1]
	v_pk_mul_f32 v[48:49], v[174:175], v[192:193] op_sel:[0,1]
	v_add_f32_dpp v42, v44, v42 quad_perm:[1,0,3,2] row_mask:0xf bank_mask:0xf bound_ctrl:1
	v_add_f32_dpp v43, v45, v43 quad_perm:[1,0,3,2] row_mask:0xf bank_mask:0xf bound_ctrl:1
	v_pk_mul_f32 v[50:51], v[172:173], v[196:197] op_sel:[0,1]
	v_add_f32_dpp v42, v42, v42 quad_perm:[2,3,0,1] row_mask:0xf bank_mask:0xf bound_ctrl:1
	v_add_f32_dpp v43, v43, v43 quad_perm:[2,3,0,1] row_mask:0xf bank_mask:0xf bound_ctrl:1
	v_pk_mul_f32 v[52:53], v[174:175], v[196:197] op_sel:[0,1]
	v_add_f32_dpp v42, v42, v42 row_ror:4 row_mask:0xf bank_mask:0xf bound_ctrl:1
	v_add_f32_dpp v43, v43, v43 row_ror:4 row_mask:0xf bank_mask:0xf bound_ctrl:1
	ds_read_b128 v[148:151], v208 offset:7680
	v_add_f32_dpp v42, v42, v42 row_ror:8 row_mask:0xf bank_mask:0xf bound_ctrl:1
	v_add_f32_dpp v43, v43, v43 row_ror:8 row_mask:0xf bank_mask:0xf bound_ctrl:1
	v_pk_fma_f32 v[46:47], v[168:169], v[42:43], v[46:47] op_sel_hi:[1,0,1]
	v_mov_b32_dpp v54, v42 quad_perm:[1,0,3,2] row_mask:0xf bank_mask:0xf bound_ctrl:1
	v_pk_fma_f32 v[48:49], v[170:171], v[42:43], v[48:49] op_sel_hi:[1,0,1]
	v_fmac_f32_e32 v43, v202, v42
	v_pk_fma_f32 v[34:35], v[34:35], v[156:157], v[46:47]
	v_pk_fma_f32 v[36:37], v[36:37], v[158:159], v[48:49]
	v_pk_fma_f32 v[50:51], v[168:169], v[54:55], v[50:51] op_sel_hi:[1,0,1]
	v_pk_fma_f32 v[52:53], v[170:171], v[54:55], v[52:53] op_sel_hi:[1,0,1]
	v_fmac_f32_e32 v43, v193, v203
	v_pk_fma_f32 v[38:39], v[38:39], v[156:157], v[50:51]
	v_pk_fma_f32 v[40:41], v[40:41], v[158:159], v[52:53]
	v_cndmask_b32_e64 v55, v55, v43, s[58:59]
	ds_read_b128 v[152:155], v208 offset:7936
	ds_read_b128 v[156:159], v208 offset:20224
	ds_read_b128 v[168:171], v208 offset:28416
	ds_read_b128 v[172:175], v208 offset:36608
	ds_read_b128 v[176:179], v209 offset:41024
	ds_read_b128 v[180:183], v210 offset:41024
	ds_read_b128 v[184:187], v211 offset:49792
	ds_read_b128 v[188:191], v211 offset:49808
	s_waitcnt lgkmcnt(9)
	v_pk_mul_f32 v[42:43], v[34:35], v[128:129] op_sel_hi:[0,1]
	v_pk_mul_f32 v[44:45], v[38:39], v[128:129] op_sel_hi:[0,1]
	v_pk_fma_f32 v[42:43], v[34:35], v[130:131], v[42:43] op_sel:[1,0,0]
	v_pk_fma_f32 v[44:45], v[38:39], v[130:131], v[44:45] op_sel:[1,0,0]
	v_pk_fma_f32 v[42:43], v[36:37], v[132:133], v[42:43] op_sel_hi:[0,1,1]
	v_pk_fma_f32 v[44:45], v[40:41], v[132:133], v[44:45] op_sel_hi:[0,1,1]
	v_pk_fma_f32 v[42:43], v[36:37], v[134:135], v[42:43] op_sel:[1,0,0]
	v_pk_fma_f32 v[44:45], v[40:41], v[134:135], v[44:45] op_sel:[1,0,0]
	v_pk_mul_f32 v[46:47], v[144:145], v[194:195] op_sel_hi:[1,0]
	v_pk_mul_f32 v[48:49], v[146:147], v[194:195] op_sel_hi:[1,0]
	v_add_f32_dpp v42, v44, v42 quad_perm:[1,0,3,2] row_mask:0xf bank_mask:0xf bound_ctrl:1
	v_add_f32_dpp v43, v45, v43 quad_perm:[1,0,3,2] row_mask:0xf bank_mask:0xf bound_ctrl:1
	v_pk_mul_f32 v[50:51], v[144:145], v[198:199] op_sel_hi:[1,0]
	v_add_f32_dpp v42, v42, v42 quad_perm:[2,3,0,1] row_mask:0xf bank_mask:0xf bound_ctrl:1
	v_add_f32_dpp v43, v43, v43 quad_perm:[2,3,0,1] row_mask:0xf bank_mask:0xf bound_ctrl:1
	v_pk_mul_f32 v[52:53], v[146:147], v[198:199] op_sel_hi:[1,0]
	v_add_f32_dpp v42, v42, v42 row_ror:4 row_mask:0xf bank_mask:0xf bound_ctrl:1
	v_add_f32_dpp v43, v43, v43 row_ror:4 row_mask:0xf bank_mask:0xf bound_ctrl:1
	ds_read_b128 v[128:131], v208 offset:8192
	v_add_f32_dpp v42, v42, v42 row_ror:8 row_mask:0xf bank_mask:0xf bound_ctrl:1
	v_add_f32_dpp v43, v43, v43 row_ror:8 row_mask:0xf bank_mask:0xf bound_ctrl:1
	v_pk_fma_f32 v[46:47], v[140:141], v[42:43], v[46:47] op_sel_hi:[1,0,1]
	v_mov_b32_dpp v54, v42 quad_perm:[1,0,3,2] row_mask:0xf bank_mask:0xf bound_ctrl:1
	v_pk_fma_f32 v[48:49], v[142:143], v[42:43], v[48:49] op_sel_hi:[1,0,1]
	v_fmac_f32_e32 v43, v204, v42
	v_pk_fma_f32 v[34:35], v[34:35], v[136:137], v[46:47]
	v_pk_fma_f32 v[36:37], v[36:37], v[138:139], v[48:49]
	v_pk_fma_f32 v[50:51], v[140:141], v[54:55], v[50:51] op_sel_hi:[1,0,1]
	v_pk_fma_f32 v[52:53], v[142:143], v[54:55], v[52:53] op_sel_hi:[1,0,1]
	v_fmac_f32_e32 v43, v194, v205
	v_pk_fma_f32 v[38:39], v[38:39], v[136:137], v[50:51]
	v_pk_fma_f32 v[40:41], v[40:41], v[138:139], v[52:53]
	v_cndmask_b32_e64 v55, v55, v43, s[60:61]
	ds_read_b128 v[132:135], v208 offset:8448
	ds_read_b128 v[136:139], v208 offset:20480
	ds_read_b128 v[140:143], v208 offset:28672
	ds_read_b128 v[144:147], v208 offset:36864
	s_waitcnt lgkmcnt(9)
	v_pk_mul_f32 v[42:43], v[34:35], v[148:149] op_sel_hi:[0,1]
	v_pk_mul_f32 v[44:45], v[38:39], v[148:149] op_sel_hi:[0,1]
	v_pk_fma_f32 v[42:43], v[34:35], v[150:151], v[42:43] op_sel:[1,0,0]
	v_pk_fma_f32 v[44:45], v[38:39], v[150:151], v[44:45] op_sel:[1,0,0]
	v_pk_fma_f32 v[42:43], v[36:37], v[152:153], v[42:43] op_sel_hi:[0,1,1]
	v_pk_fma_f32 v[44:45], v[40:41], v[152:153], v[44:45] op_sel_hi:[0,1,1]
	v_pk_fma_f32 v[42:43], v[36:37], v[154:155], v[42:43] op_sel:[1,0,0]
	v_pk_fma_f32 v[44:45], v[40:41], v[154:155], v[44:45] op_sel:[1,0,0]
	v_pk_mul_f32 v[46:47], v[172:173], v[194:195] op_sel:[0,1]
	v_pk_mul_f32 v[48:49], v[174:175], v[194:195] op_sel:[0,1]
	v_add_f32_dpp v42, v44, v42 quad_perm:[1,0,3,2] row_mask:0xf bank_mask:0xf bound_ctrl:1
	v_add_f32_dpp v43, v45, v43 quad_perm:[1,0,3,2] row_mask:0xf bank_mask:0xf bound_ctrl:1
	v_pk_mul_f32 v[50:51], v[172:173], v[198:199] op_sel:[0,1]
	v_add_f32_dpp v42, v42, v42 quad_perm:[2,3,0,1] row_mask:0xf bank_mask:0xf bound_ctrl:1
	v_add_f32_dpp v43, v43, v43 quad_perm:[2,3,0,1] row_mask:0xf bank_mask:0xf bound_ctrl:1
	v_pk_mul_f32 v[52:53], v[174:175], v[198:199] op_sel:[0,1]
	v_add_f32_dpp v42, v42, v42 row_ror:4 row_mask:0xf bank_mask:0xf bound_ctrl:1
	v_add_f32_dpp v43, v43, v43 row_ror:4 row_mask:0xf bank_mask:0xf bound_ctrl:1
	ds_read_b128 v[148:151], v208 offset:8704
	v_add_f32_dpp v42, v42, v42 row_ror:8 row_mask:0xf bank_mask:0xf bound_ctrl:1
	v_add_f32_dpp v43, v43, v43 row_ror:8 row_mask:0xf bank_mask:0xf bound_ctrl:1
	v_pk_fma_f32 v[46:47], v[168:169], v[42:43], v[46:47] op_sel_hi:[1,0,1]
	v_mov_b32_dpp v54, v42 quad_perm:[1,0,3,2] row_mask:0xf bank_mask:0xf bound_ctrl:1
	v_pk_fma_f32 v[48:49], v[170:171], v[42:43], v[48:49] op_sel_hi:[1,0,1]
	v_fmac_f32_e32 v43, v206, v42
	v_pk_fma_f32 v[34:35], v[34:35], v[156:157], v[46:47]
	v_pk_fma_f32 v[36:37], v[36:37], v[158:159], v[48:49]
	v_pk_fma_f32 v[50:51], v[168:169], v[54:55], v[50:51] op_sel_hi:[1,0,1]
	v_pk_fma_f32 v[52:53], v[170:171], v[54:55], v[52:53] op_sel_hi:[1,0,1]
	v_fmac_f32_e32 v43, v195, v207
	v_pk_fma_f32 v[38:39], v[38:39], v[156:157], v[50:51]
	v_pk_fma_f32 v[40:41], v[40:41], v[158:159], v[52:53]
	v_cndmask_b32_e64 v55, v55, v43, s[62:63]
	ds_write_b32 v212, v55 offset:1024
	ds_read_b128 v[152:155], v208 offset:8960
	ds_read_b128 v[156:159], v208 offset:20736
	ds_read_b128 v[168:171], v208 offset:28928
	ds_read_b128 v[172:175], v208 offset:37120
	s_waitcnt lgkmcnt(6)
	v_pk_mul_f32 v[42:43], v[34:35], v[128:129] op_sel_hi:[0,1]
	v_pk_mul_f32 v[44:45], v[38:39], v[128:129] op_sel_hi:[0,1]
	v_pk_fma_f32 v[42:43], v[34:35], v[130:131], v[42:43] op_sel:[1,0,0]
	v_pk_fma_f32 v[44:45], v[38:39], v[130:131], v[44:45] op_sel:[1,0,0]
	v_pk_fma_f32 v[42:43], v[36:37], v[132:133], v[42:43] op_sel_hi:[0,1,1]
	v_pk_fma_f32 v[44:45], v[40:41], v[132:133], v[44:45] op_sel_hi:[0,1,1]
	v_pk_fma_f32 v[42:43], v[36:37], v[134:135], v[42:43] op_sel:[1,0,0]
	v_pk_fma_f32 v[44:45], v[40:41], v[134:135], v[44:45] op_sel:[1,0,0]
	v_pk_mul_f32 v[46:47], v[144:145], v[176:177] op_sel_hi:[1,0]
	v_pk_mul_f32 v[48:49], v[146:147], v[176:177] op_sel_hi:[1,0]
	v_add_f32_dpp v42, v44, v42 quad_perm:[1,0,3,2] row_mask:0xf bank_mask:0xf bound_ctrl:1
	v_add_f32_dpp v43, v45, v43 quad_perm:[1,0,3,2] row_mask:0xf bank_mask:0xf bound_ctrl:1
	v_pk_mul_f32 v[50:51], v[144:145], v[180:181] op_sel_hi:[1,0]
	v_add_f32_dpp v42, v42, v42 quad_perm:[2,3,0,1] row_mask:0xf bank_mask:0xf bound_ctrl:1
	v_add_f32_dpp v43, v43, v43 quad_perm:[2,3,0,1] row_mask:0xf bank_mask:0xf bound_ctrl:1
	v_pk_mul_f32 v[52:53], v[146:147], v[180:181] op_sel_hi:[1,0]
	v_add_f32_dpp v42, v42, v42 row_ror:4 row_mask:0xf bank_mask:0xf bound_ctrl:1
	v_add_f32_dpp v43, v43, v43 row_ror:4 row_mask:0xf bank_mask:0xf bound_ctrl:1
	ds_read_b128 v[128:131], v208 offset:9216
	v_add_f32_dpp v42, v42, v42 row_ror:8 row_mask:0xf bank_mask:0xf bound_ctrl:1
	v_add_f32_dpp v43, v43, v43 row_ror:8 row_mask:0xf bank_mask:0xf bound_ctrl:1
	v_pk_fma_f32 v[46:47], v[140:141], v[42:43], v[46:47] op_sel_hi:[1,0,1]
	v_mov_b32_dpp v54, v42 quad_perm:[1,0,3,2] row_mask:0xf bank_mask:0xf bound_ctrl:1
	v_pk_fma_f32 v[48:49], v[142:143], v[42:43], v[48:49] op_sel_hi:[1,0,1]
	v_fmac_f32_e32 v43, v184, v42
	v_pk_fma_f32 v[34:35], v[34:35], v[136:137], v[46:47]
	v_pk_fma_f32 v[36:37], v[36:37], v[138:139], v[48:49]
	v_pk_fma_f32 v[50:51], v[140:141], v[54:55], v[50:51] op_sel_hi:[1,0,1]
	v_pk_fma_f32 v[52:53], v[142:143], v[54:55], v[52:53] op_sel_hi:[1,0,1]
	v_fmac_f32_e32 v43, v176, v185
	v_pk_fma_f32 v[38:39], v[38:39], v[136:137], v[50:51]
	v_pk_fma_f32 v[40:41], v[40:41], v[138:139], v[52:53]
	v_cndmask_b32_e64 v55, 0, v43, s[48:49]
	ds_read_b128 v[132:135], v208 offset:9472
	ds_read_b128 v[136:139], v208 offset:20992
	ds_read_b128 v[140:143], v208 offset:29184
	ds_read_b128 v[144:147], v208 offset:37376
	s_waitcnt lgkmcnt(5)
	v_pk_mul_f32 v[42:43], v[34:35], v[148:149] op_sel_hi:[0,1]
	v_pk_mul_f32 v[44:45], v[38:39], v[148:149] op_sel_hi:[0,1]
	v_pk_fma_f32 v[42:43], v[34:35], v[150:151], v[42:43] op_sel:[1,0,0]
	v_pk_fma_f32 v[44:45], v[38:39], v[150:151], v[44:45] op_sel:[1,0,0]
	v_pk_fma_f32 v[42:43], v[36:37], v[152:153], v[42:43] op_sel_hi:[0,1,1]
	v_pk_fma_f32 v[44:45], v[40:41], v[152:153], v[44:45] op_sel_hi:[0,1,1]
	v_pk_fma_f32 v[42:43], v[36:37], v[154:155], v[42:43] op_sel:[1,0,0]
	v_pk_fma_f32 v[44:45], v[40:41], v[154:155], v[44:45] op_sel:[1,0,0]
	v_pk_mul_f32 v[46:47], v[172:173], v[176:177] op_sel:[0,1]
	v_pk_mul_f32 v[48:49], v[174:175], v[176:177] op_sel:[0,1]
	v_add_f32_dpp v42, v44, v42 quad_perm:[1,0,3,2] row_mask:0xf bank_mask:0xf bound_ctrl:1
	v_add_f32_dpp v43, v45, v43 quad_perm:[1,0,3,2] row_mask:0xf bank_mask:0xf bound_ctrl:1
	v_pk_mul_f32 v[50:51], v[172:173], v[180:181] op_sel:[0,1]
	v_add_f32_dpp v42, v42, v42 quad_perm:[2,3,0,1] row_mask:0xf bank_mask:0xf bound_ctrl:1
	v_add_f32_dpp v43, v43, v43 quad_perm:[2,3,0,1] row_mask:0xf bank_mask:0xf bound_ctrl:1
	v_pk_mul_f32 v[52:53], v[174:175], v[180:181] op_sel:[0,1]
	v_add_f32_dpp v42, v42, v42 row_ror:4 row_mask:0xf bank_mask:0xf bound_ctrl:1
	v_add_f32_dpp v43, v43, v43 row_ror:4 row_mask:0xf bank_mask:0xf bound_ctrl:1
	ds_read_b128 v[148:151], v208 offset:9728
	v_add_f32_dpp v42, v42, v42 row_ror:8 row_mask:0xf bank_mask:0xf bound_ctrl:1
	v_add_f32_dpp v43, v43, v43 row_ror:8 row_mask:0xf bank_mask:0xf bound_ctrl:1
	v_pk_fma_f32 v[46:47], v[168:169], v[42:43], v[46:47] op_sel_hi:[1,0,1]
	v_mov_b32_dpp v54, v42 quad_perm:[1,0,3,2] row_mask:0xf bank_mask:0xf bound_ctrl:1
	v_pk_fma_f32 v[48:49], v[170:171], v[42:43], v[48:49] op_sel_hi:[1,0,1]
	v_fmac_f32_e32 v43, v186, v42
	v_pk_fma_f32 v[34:35], v[34:35], v[156:157], v[46:47]
	v_pk_fma_f32 v[36:37], v[36:37], v[158:159], v[48:49]
	v_pk_fma_f32 v[50:51], v[168:169], v[54:55], v[50:51] op_sel_hi:[1,0,1]
	v_pk_fma_f32 v[52:53], v[170:171], v[54:55], v[52:53] op_sel_hi:[1,0,1]
	v_fmac_f32_e32 v43, v177, v187
	v_pk_fma_f32 v[38:39], v[38:39], v[156:157], v[50:51]
	v_pk_fma_f32 v[40:41], v[40:41], v[158:159], v[52:53]
	v_cndmask_b32_e64 v55, v55, v43, s[50:51]
	ds_read_b128 v[152:155], v208 offset:9984
	ds_read_b128 v[156:159], v208 offset:21248
	ds_read_b128 v[168:171], v208 offset:29440
	ds_read_b128 v[172:175], v208 offset:37632
	ds_read_b128 v[192:195], v209 offset:41040
	ds_read_b128 v[196:199], v210 offset:41040
	ds_read_b128 v[200:203], v211 offset:49824
	ds_read_b128 v[204:207], v211 offset:49840
	s_waitcnt lgkmcnt(9)
	v_pk_mul_f32 v[42:43], v[34:35], v[128:129] op_sel_hi:[0,1]
	v_pk_mul_f32 v[44:45], v[38:39], v[128:129] op_sel_hi:[0,1]
	v_pk_fma_f32 v[42:43], v[34:35], v[130:131], v[42:43] op_sel:[1,0,0]
	v_pk_fma_f32 v[44:45], v[38:39], v[130:131], v[44:45] op_sel:[1,0,0]
	v_pk_fma_f32 v[42:43], v[36:37], v[132:133], v[42:43] op_sel_hi:[0,1,1]
	v_pk_fma_f32 v[44:45], v[40:41], v[132:133], v[44:45] op_sel_hi:[0,1,1]
	v_pk_fma_f32 v[42:43], v[36:37], v[134:135], v[42:43] op_sel:[1,0,0]
	v_pk_fma_f32 v[44:45], v[40:41], v[134:135], v[44:45] op_sel:[1,0,0]
	v_pk_mul_f32 v[46:47], v[144:145], v[178:179] op_sel_hi:[1,0]
	v_pk_mul_f32 v[48:49], v[146:147], v[178:179] op_sel_hi:[1,0]
	v_add_f32_dpp v42, v44, v42 quad_perm:[1,0,3,2] row_mask:0xf bank_mask:0xf bound_ctrl:1
	v_add_f32_dpp v43, v45, v43 quad_perm:[1,0,3,2] row_mask:0xf bank_mask:0xf bound_ctrl:1
	v_pk_mul_f32 v[50:51], v[144:145], v[182:183] op_sel_hi:[1,0]
	v_add_f32_dpp v42, v42, v42 quad_perm:[2,3,0,1] row_mask:0xf bank_mask:0xf bound_ctrl:1
	v_add_f32_dpp v43, v43, v43 quad_perm:[2,3,0,1] row_mask:0xf bank_mask:0xf bound_ctrl:1
	v_pk_mul_f32 v[52:53], v[146:147], v[182:183] op_sel_hi:[1,0]
	v_add_f32_dpp v42, v42, v42 row_ror:4 row_mask:0xf bank_mask:0xf bound_ctrl:1
	v_add_f32_dpp v43, v43, v43 row_ror:4 row_mask:0xf bank_mask:0xf bound_ctrl:1
	ds_read_b128 v[128:131], v208 offset:10240
	v_add_f32_dpp v42, v42, v42 row_ror:8 row_mask:0xf bank_mask:0xf bound_ctrl:1
	v_add_f32_dpp v43, v43, v43 row_ror:8 row_mask:0xf bank_mask:0xf bound_ctrl:1
	v_pk_fma_f32 v[46:47], v[140:141], v[42:43], v[46:47] op_sel_hi:[1,0,1]
	v_mov_b32_dpp v54, v42 quad_perm:[1,0,3,2] row_mask:0xf bank_mask:0xf bound_ctrl:1
	v_pk_fma_f32 v[48:49], v[142:143], v[42:43], v[48:49] op_sel_hi:[1,0,1]
	v_fmac_f32_e32 v43, v188, v42
	v_pk_fma_f32 v[34:35], v[34:35], v[136:137], v[46:47]
	v_pk_fma_f32 v[36:37], v[36:37], v[138:139], v[48:49]
	v_pk_fma_f32 v[50:51], v[140:141], v[54:55], v[50:51] op_sel_hi:[1,0,1]
	v_pk_fma_f32 v[52:53], v[142:143], v[54:55], v[52:53] op_sel_hi:[1,0,1]
	v_fmac_f32_e32 v43, v178, v189
	v_pk_fma_f32 v[38:39], v[38:39], v[136:137], v[50:51]
	v_pk_fma_f32 v[40:41], v[40:41], v[138:139], v[52:53]
	v_cndmask_b32_e64 v55, v55, v43, s[52:53]
	ds_read_b128 v[132:135], v208 offset:10496
	ds_read_b128 v[136:139], v208 offset:21504
	ds_read_b128 v[140:143], v208 offset:29696
	ds_read_b128 v[144:147], v208 offset:37888
	s_waitcnt lgkmcnt(9)
	v_pk_mul_f32 v[42:43], v[34:35], v[148:149] op_sel_hi:[0,1]
	v_pk_mul_f32 v[44:45], v[38:39], v[148:149] op_sel_hi:[0,1]
	v_pk_fma_f32 v[42:43], v[34:35], v[150:151], v[42:43] op_sel:[1,0,0]
	v_pk_fma_f32 v[44:45], v[38:39], v[150:151], v[44:45] op_sel:[1,0,0]
	v_pk_fma_f32 v[42:43], v[36:37], v[152:153], v[42:43] op_sel_hi:[0,1,1]
	v_pk_fma_f32 v[44:45], v[40:41], v[152:153], v[44:45] op_sel_hi:[0,1,1]
	v_pk_fma_f32 v[42:43], v[36:37], v[154:155], v[42:43] op_sel:[1,0,0]
	v_pk_fma_f32 v[44:45], v[40:41], v[154:155], v[44:45] op_sel:[1,0,0]
	v_pk_mul_f32 v[46:47], v[172:173], v[178:179] op_sel:[0,1]
	v_pk_mul_f32 v[48:49], v[174:175], v[178:179] op_sel:[0,1]
	v_add_f32_dpp v42, v44, v42 quad_perm:[1,0,3,2] row_mask:0xf bank_mask:0xf bound_ctrl:1
	v_add_f32_dpp v43, v45, v43 quad_perm:[1,0,3,2] row_mask:0xf bank_mask:0xf bound_ctrl:1
	v_pk_mul_f32 v[50:51], v[172:173], v[182:183] op_sel:[0,1]
	v_add_f32_dpp v42, v42, v42 quad_perm:[2,3,0,1] row_mask:0xf bank_mask:0xf bound_ctrl:1
	v_add_f32_dpp v43, v43, v43 quad_perm:[2,3,0,1] row_mask:0xf bank_mask:0xf bound_ctrl:1
	v_pk_mul_f32 v[52:53], v[174:175], v[182:183] op_sel:[0,1]
	v_add_f32_dpp v42, v42, v42 row_ror:4 row_mask:0xf bank_mask:0xf bound_ctrl:1
	v_add_f32_dpp v43, v43, v43 row_ror:4 row_mask:0xf bank_mask:0xf bound_ctrl:1
	ds_read_b128 v[148:151], v208 offset:10752
	v_add_f32_dpp v42, v42, v42 row_ror:8 row_mask:0xf bank_mask:0xf bound_ctrl:1
	v_add_f32_dpp v43, v43, v43 row_ror:8 row_mask:0xf bank_mask:0xf bound_ctrl:1
	v_pk_fma_f32 v[46:47], v[168:169], v[42:43], v[46:47] op_sel_hi:[1,0,1]
	v_mov_b32_dpp v54, v42 quad_perm:[1,0,3,2] row_mask:0xf bank_mask:0xf bound_ctrl:1
	v_pk_fma_f32 v[48:49], v[170:171], v[42:43], v[48:49] op_sel_hi:[1,0,1]
	v_fmac_f32_e32 v43, v190, v42
	v_pk_fma_f32 v[34:35], v[34:35], v[156:157], v[46:47]
	v_pk_fma_f32 v[36:37], v[36:37], v[158:159], v[48:49]
	v_pk_fma_f32 v[50:51], v[168:169], v[54:55], v[50:51] op_sel_hi:[1,0,1]
	v_pk_fma_f32 v[52:53], v[170:171], v[54:55], v[52:53] op_sel_hi:[1,0,1]
	v_fmac_f32_e32 v43, v179, v191
	v_pk_fma_f32 v[38:39], v[38:39], v[156:157], v[50:51]
	v_pk_fma_f32 v[40:41], v[40:41], v[158:159], v[52:53]
	v_cndmask_b32_e64 v55, v55, v43, s[54:55]
	ds_read_b128 v[152:155], v208 offset:11008
	ds_read_b128 v[156:159], v208 offset:21760
	ds_read_b128 v[168:171], v208 offset:29952
	ds_read_b128 v[172:175], v208 offset:38144
	s_waitcnt lgkmcnt(5)
	v_pk_mul_f32 v[42:43], v[34:35], v[128:129] op_sel_hi:[0,1]
	v_pk_mul_f32 v[44:45], v[38:39], v[128:129] op_sel_hi:[0,1]
	v_pk_fma_f32 v[42:43], v[34:35], v[130:131], v[42:43] op_sel:[1,0,0]
	v_pk_fma_f32 v[44:45], v[38:39], v[130:131], v[44:45] op_sel:[1,0,0]
	v_pk_fma_f32 v[42:43], v[36:37], v[132:133], v[42:43] op_sel_hi:[0,1,1]
	v_pk_fma_f32 v[44:45], v[40:41], v[132:133], v[44:45] op_sel_hi:[0,1,1]
	v_pk_fma_f32 v[42:43], v[36:37], v[134:135], v[42:43] op_sel:[1,0,0]
	v_pk_fma_f32 v[44:45], v[40:41], v[134:135], v[44:45] op_sel:[1,0,0]
	v_pk_mul_f32 v[46:47], v[144:145], v[192:193] op_sel_hi:[1,0]
	v_pk_mul_f32 v[48:49], v[146:147], v[192:193] op_sel_hi:[1,0]
	v_add_f32_dpp v42, v44, v42 quad_perm:[1,0,3,2] row_mask:0xf bank_mask:0xf bound_ctrl:1
	v_add_f32_dpp v43, v45, v43 quad_perm:[1,0,3,2] row_mask:0xf bank_mask:0xf bound_ctrl:1
	v_pk_mul_f32 v[50:51], v[144:145], v[196:197] op_sel_hi:[1,0]
	v_add_f32_dpp v42, v42, v42 quad_perm:[2,3,0,1] row_mask:0xf bank_mask:0xf bound_ctrl:1
	v_add_f32_dpp v43, v43, v43 quad_perm:[2,3,0,1] row_mask:0xf bank_mask:0xf bound_ctrl:1
	v_pk_mul_f32 v[52:53], v[146:147], v[196:197] op_sel_hi:[1,0]
	v_add_f32_dpp v42, v42, v42 row_ror:4 row_mask:0xf bank_mask:0xf bound_ctrl:1
	v_add_f32_dpp v43, v43, v43 row_ror:4 row_mask:0xf bank_mask:0xf bound_ctrl:1
	ds_read_b128 v[128:131], v208 offset:11264
	v_add_f32_dpp v42, v42, v42 row_ror:8 row_mask:0xf bank_mask:0xf bound_ctrl:1
	v_add_f32_dpp v43, v43, v43 row_ror:8 row_mask:0xf bank_mask:0xf bound_ctrl:1
	v_pk_fma_f32 v[46:47], v[140:141], v[42:43], v[46:47] op_sel_hi:[1,0,1]
	v_mov_b32_dpp v54, v42 quad_perm:[1,0,3,2] row_mask:0xf bank_mask:0xf bound_ctrl:1
	v_pk_fma_f32 v[48:49], v[142:143], v[42:43], v[48:49] op_sel_hi:[1,0,1]
	v_fmac_f32_e32 v43, v200, v42
	v_pk_fma_f32 v[34:35], v[34:35], v[136:137], v[46:47]
	v_pk_fma_f32 v[36:37], v[36:37], v[138:139], v[48:49]
	v_pk_fma_f32 v[50:51], v[140:141], v[54:55], v[50:51] op_sel_hi:[1,0,1]
	v_pk_fma_f32 v[52:53], v[142:143], v[54:55], v[52:53] op_sel_hi:[1,0,1]
	v_fmac_f32_e32 v43, v192, v201
	v_pk_fma_f32 v[38:39], v[38:39], v[136:137], v[50:51]
	v_pk_fma_f32 v[40:41], v[40:41], v[138:139], v[52:53]
	v_cndmask_b32_e64 v55, v55, v43, s[56:57]
	ds_read_b128 v[132:135], v208 offset:11520
	ds_read_b128 v[136:139], v208 offset:22016
	ds_read_b128 v[140:143], v208 offset:30208
	ds_read_b128 v[144:147], v208 offset:38400
	s_waitcnt lgkmcnt(5)
	v_pk_mul_f32 v[42:43], v[34:35], v[148:149] op_sel_hi:[0,1]
	v_pk_mul_f32 v[44:45], v[38:39], v[148:149] op_sel_hi:[0,1]
	v_pk_fma_f32 v[42:43], v[34:35], v[150:151], v[42:43] op_sel:[1,0,0]
	v_pk_fma_f32 v[44:45], v[38:39], v[150:151], v[44:45] op_sel:[1,0,0]
	v_pk_fma_f32 v[42:43], v[36:37], v[152:153], v[42:43] op_sel_hi:[0,1,1]
	v_pk_fma_f32 v[44:45], v[40:41], v[152:153], v[44:45] op_sel_hi:[0,1,1]
	v_pk_fma_f32 v[42:43], v[36:37], v[154:155], v[42:43] op_sel:[1,0,0]
	v_pk_fma_f32 v[44:45], v[40:41], v[154:155], v[44:45] op_sel:[1,0,0]
	v_pk_mul_f32 v[46:47], v[172:173], v[192:193] op_sel:[0,1]
	v_pk_mul_f32 v[48:49], v[174:175], v[192:193] op_sel:[0,1]
	v_add_f32_dpp v42, v44, v42 quad_perm:[1,0,3,2] row_mask:0xf bank_mask:0xf bound_ctrl:1
	v_add_f32_dpp v43, v45, v43 quad_perm:[1,0,3,2] row_mask:0xf bank_mask:0xf bound_ctrl:1
	v_pk_mul_f32 v[50:51], v[172:173], v[196:197] op_sel:[0,1]
	v_add_f32_dpp v42, v42, v42 quad_perm:[2,3,0,1] row_mask:0xf bank_mask:0xf bound_ctrl:1
	v_add_f32_dpp v43, v43, v43 quad_perm:[2,3,0,1] row_mask:0xf bank_mask:0xf bound_ctrl:1
	v_pk_mul_f32 v[52:53], v[174:175], v[196:197] op_sel:[0,1]
	v_add_f32_dpp v42, v42, v42 row_ror:4 row_mask:0xf bank_mask:0xf bound_ctrl:1
	v_add_f32_dpp v43, v43, v43 row_ror:4 row_mask:0xf bank_mask:0xf bound_ctrl:1
	ds_read_b128 v[148:151], v208 offset:11776
	v_add_f32_dpp v42, v42, v42 row_ror:8 row_mask:0xf bank_mask:0xf bound_ctrl:1
	v_add_f32_dpp v43, v43, v43 row_ror:8 row_mask:0xf bank_mask:0xf bound_ctrl:1
	v_pk_fma_f32 v[46:47], v[168:169], v[42:43], v[46:47] op_sel_hi:[1,0,1]
	v_mov_b32_dpp v54, v42 quad_perm:[1,0,3,2] row_mask:0xf bank_mask:0xf bound_ctrl:1
	v_pk_fma_f32 v[48:49], v[170:171], v[42:43], v[48:49] op_sel_hi:[1,0,1]
	v_fmac_f32_e32 v43, v202, v42
	v_pk_fma_f32 v[34:35], v[34:35], v[156:157], v[46:47]
	v_pk_fma_f32 v[36:37], v[36:37], v[158:159], v[48:49]
	v_pk_fma_f32 v[50:51], v[168:169], v[54:55], v[50:51] op_sel_hi:[1,0,1]
	v_pk_fma_f32 v[52:53], v[170:171], v[54:55], v[52:53] op_sel_hi:[1,0,1]
	v_fmac_f32_e32 v43, v193, v203
	v_pk_fma_f32 v[38:39], v[38:39], v[156:157], v[50:51]
	v_pk_fma_f32 v[40:41], v[40:41], v[158:159], v[52:53]
	v_cndmask_b32_e64 v55, v55, v43, s[58:59]
	ds_read_b128 v[152:155], v208 offset:12032
	ds_read_b128 v[156:159], v208 offset:22272
	ds_read_b128 v[168:171], v208 offset:30464
	ds_read_b128 v[172:175], v208 offset:38656
	ds_read_b128 v[176:179], v209 offset:41056
	ds_read_b128 v[180:183], v210 offset:41056
	ds_read_b128 v[184:187], v211 offset:49856
	ds_read_b128 v[188:191], v211 offset:49872
	s_waitcnt lgkmcnt(9)
	v_pk_mul_f32 v[42:43], v[34:35], v[128:129] op_sel_hi:[0,1]
	v_pk_mul_f32 v[44:45], v[38:39], v[128:129] op_sel_hi:[0,1]
	v_pk_fma_f32 v[42:43], v[34:35], v[130:131], v[42:43] op_sel:[1,0,0]
	v_pk_fma_f32 v[44:45], v[38:39], v[130:131], v[44:45] op_sel:[1,0,0]
	v_pk_fma_f32 v[42:43], v[36:37], v[132:133], v[42:43] op_sel_hi:[0,1,1]
	v_pk_fma_f32 v[44:45], v[40:41], v[132:133], v[44:45] op_sel_hi:[0,1,1]
	v_pk_fma_f32 v[42:43], v[36:37], v[134:135], v[42:43] op_sel:[1,0,0]
	v_pk_fma_f32 v[44:45], v[40:41], v[134:135], v[44:45] op_sel:[1,0,0]
	v_pk_mul_f32 v[46:47], v[144:145], v[194:195] op_sel_hi:[1,0]
	v_pk_mul_f32 v[48:49], v[146:147], v[194:195] op_sel_hi:[1,0]
	v_add_f32_dpp v42, v44, v42 quad_perm:[1,0,3,2] row_mask:0xf bank_mask:0xf bound_ctrl:1
	v_add_f32_dpp v43, v45, v43 quad_perm:[1,0,3,2] row_mask:0xf bank_mask:0xf bound_ctrl:1
	v_pk_mul_f32 v[50:51], v[144:145], v[198:199] op_sel_hi:[1,0]
	v_add_f32_dpp v42, v42, v42 quad_perm:[2,3,0,1] row_mask:0xf bank_mask:0xf bound_ctrl:1
	v_add_f32_dpp v43, v43, v43 quad_perm:[2,3,0,1] row_mask:0xf bank_mask:0xf bound_ctrl:1
	v_pk_mul_f32 v[52:53], v[146:147], v[198:199] op_sel_hi:[1,0]
	v_add_f32_dpp v42, v42, v42 row_ror:4 row_mask:0xf bank_mask:0xf bound_ctrl:1
	v_add_f32_dpp v43, v43, v43 row_ror:4 row_mask:0xf bank_mask:0xf bound_ctrl:1
	ds_read_b128 v[128:131], v208 offset:12288
	v_add_f32_dpp v42, v42, v42 row_ror:8 row_mask:0xf bank_mask:0xf bound_ctrl:1
	v_add_f32_dpp v43, v43, v43 row_ror:8 row_mask:0xf bank_mask:0xf bound_ctrl:1
	v_pk_fma_f32 v[46:47], v[140:141], v[42:43], v[46:47] op_sel_hi:[1,0,1]
	v_mov_b32_dpp v54, v42 quad_perm:[1,0,3,2] row_mask:0xf bank_mask:0xf bound_ctrl:1
	v_pk_fma_f32 v[48:49], v[142:143], v[42:43], v[48:49] op_sel_hi:[1,0,1]
	v_fmac_f32_e32 v43, v204, v42
	v_pk_fma_f32 v[34:35], v[34:35], v[136:137], v[46:47]
	v_pk_fma_f32 v[36:37], v[36:37], v[138:139], v[48:49]
	v_pk_fma_f32 v[50:51], v[140:141], v[54:55], v[50:51] op_sel_hi:[1,0,1]
	v_pk_fma_f32 v[52:53], v[142:143], v[54:55], v[52:53] op_sel_hi:[1,0,1]
	v_fmac_f32_e32 v43, v194, v205
	v_pk_fma_f32 v[38:39], v[38:39], v[136:137], v[50:51]
	v_pk_fma_f32 v[40:41], v[40:41], v[138:139], v[52:53]
	v_cndmask_b32_e64 v55, v55, v43, s[60:61]
	ds_read_b128 v[132:135], v208 offset:12544
	ds_read_b128 v[136:139], v208 offset:22528
	ds_read_b128 v[140:143], v208 offset:30720
	ds_read_b128 v[144:147], v208 offset:38912
	s_waitcnt lgkmcnt(9)
	v_pk_mul_f32 v[42:43], v[34:35], v[148:149] op_sel_hi:[0,1]
	v_pk_mul_f32 v[44:45], v[38:39], v[148:149] op_sel_hi:[0,1]
	v_pk_fma_f32 v[42:43], v[34:35], v[150:151], v[42:43] op_sel:[1,0,0]
	v_pk_fma_f32 v[44:45], v[38:39], v[150:151], v[44:45] op_sel:[1,0,0]
	v_pk_fma_f32 v[42:43], v[36:37], v[152:153], v[42:43] op_sel_hi:[0,1,1]
	v_pk_fma_f32 v[44:45], v[40:41], v[152:153], v[44:45] op_sel_hi:[0,1,1]
	v_pk_fma_f32 v[42:43], v[36:37], v[154:155], v[42:43] op_sel:[1,0,0]
	v_pk_fma_f32 v[44:45], v[40:41], v[154:155], v[44:45] op_sel:[1,0,0]
	v_pk_mul_f32 v[46:47], v[172:173], v[194:195] op_sel:[0,1]
	v_pk_mul_f32 v[48:49], v[174:175], v[194:195] op_sel:[0,1]
	v_add_f32_dpp v42, v44, v42 quad_perm:[1,0,3,2] row_mask:0xf bank_mask:0xf bound_ctrl:1
	v_add_f32_dpp v43, v45, v43 quad_perm:[1,0,3,2] row_mask:0xf bank_mask:0xf bound_ctrl:1
	v_pk_mul_f32 v[50:51], v[172:173], v[198:199] op_sel:[0,1]
	v_add_f32_dpp v42, v42, v42 quad_perm:[2,3,0,1] row_mask:0xf bank_mask:0xf bound_ctrl:1
	v_add_f32_dpp v43, v43, v43 quad_perm:[2,3,0,1] row_mask:0xf bank_mask:0xf bound_ctrl:1
	v_pk_mul_f32 v[52:53], v[174:175], v[198:199] op_sel:[0,1]
	v_add_f32_dpp v42, v42, v42 row_ror:4 row_mask:0xf bank_mask:0xf bound_ctrl:1
	v_add_f32_dpp v43, v43, v43 row_ror:4 row_mask:0xf bank_mask:0xf bound_ctrl:1
	ds_read_b128 v[148:151], v208 offset:12800
	v_add_f32_dpp v42, v42, v42 row_ror:8 row_mask:0xf bank_mask:0xf bound_ctrl:1
	v_add_f32_dpp v43, v43, v43 row_ror:8 row_mask:0xf bank_mask:0xf bound_ctrl:1
	v_pk_fma_f32 v[46:47], v[168:169], v[42:43], v[46:47] op_sel_hi:[1,0,1]
	v_mov_b32_dpp v54, v42 quad_perm:[1,0,3,2] row_mask:0xf bank_mask:0xf bound_ctrl:1
	v_pk_fma_f32 v[48:49], v[170:171], v[42:43], v[48:49] op_sel_hi:[1,0,1]
	v_fmac_f32_e32 v43, v206, v42
	v_pk_fma_f32 v[34:35], v[34:35], v[156:157], v[46:47]
	v_pk_fma_f32 v[36:37], v[36:37], v[158:159], v[48:49]
	v_pk_fma_f32 v[50:51], v[168:169], v[54:55], v[50:51] op_sel_hi:[1,0,1]
	v_pk_fma_f32 v[52:53], v[170:171], v[54:55], v[52:53] op_sel_hi:[1,0,1]
	v_fmac_f32_e32 v43, v195, v207
	v_pk_fma_f32 v[38:39], v[38:39], v[156:157], v[50:51]
	v_pk_fma_f32 v[40:41], v[40:41], v[158:159], v[52:53]
	v_cndmask_b32_e64 v55, v55, v43, s[62:63]
	ds_write_b32 v212, v55 offset:2048
	ds_read_b128 v[152:155], v208 offset:13056
	ds_read_b128 v[156:159], v208 offset:22784
	ds_read_b128 v[168:171], v208 offset:30976
	ds_read_b128 v[172:175], v208 offset:39168
	s_waitcnt lgkmcnt(6)
	v_pk_mul_f32 v[42:43], v[34:35], v[128:129] op_sel_hi:[0,1]
	v_pk_mul_f32 v[44:45], v[38:39], v[128:129] op_sel_hi:[0,1]
	v_pk_fma_f32 v[42:43], v[34:35], v[130:131], v[42:43] op_sel:[1,0,0]
	v_pk_fma_f32 v[44:45], v[38:39], v[130:131], v[44:45] op_sel:[1,0,0]
	v_pk_fma_f32 v[42:43], v[36:37], v[132:133], v[42:43] op_sel_hi:[0,1,1]
	v_pk_fma_f32 v[44:45], v[40:41], v[132:133], v[44:45] op_sel_hi:[0,1,1]
	v_pk_fma_f32 v[42:43], v[36:37], v[134:135], v[42:43] op_sel:[1,0,0]
	v_pk_fma_f32 v[44:45], v[40:41], v[134:135], v[44:45] op_sel:[1,0,0]
	v_pk_mul_f32 v[46:47], v[144:145], v[176:177] op_sel_hi:[1,0]
	v_pk_mul_f32 v[48:49], v[146:147], v[176:177] op_sel_hi:[1,0]
	v_add_f32_dpp v42, v44, v42 quad_perm:[1,0,3,2] row_mask:0xf bank_mask:0xf bound_ctrl:1
	v_add_f32_dpp v43, v45, v43 quad_perm:[1,0,3,2] row_mask:0xf bank_mask:0xf bound_ctrl:1
	v_pk_mul_f32 v[50:51], v[144:145], v[180:181] op_sel_hi:[1,0]
	v_add_f32_dpp v42, v42, v42 quad_perm:[2,3,0,1] row_mask:0xf bank_mask:0xf bound_ctrl:1
	v_add_f32_dpp v43, v43, v43 quad_perm:[2,3,0,1] row_mask:0xf bank_mask:0xf bound_ctrl:1
	v_pk_mul_f32 v[52:53], v[146:147], v[180:181] op_sel_hi:[1,0]
	v_add_f32_dpp v42, v42, v42 row_ror:4 row_mask:0xf bank_mask:0xf bound_ctrl:1
	v_add_f32_dpp v43, v43, v43 row_ror:4 row_mask:0xf bank_mask:0xf bound_ctrl:1
	ds_read_b128 v[128:131], v208 offset:13312
	v_add_f32_dpp v42, v42, v42 row_ror:8 row_mask:0xf bank_mask:0xf bound_ctrl:1
	v_add_f32_dpp v43, v43, v43 row_ror:8 row_mask:0xf bank_mask:0xf bound_ctrl:1
	v_pk_fma_f32 v[46:47], v[140:141], v[42:43], v[46:47] op_sel_hi:[1,0,1]
	v_mov_b32_dpp v54, v42 quad_perm:[1,0,3,2] row_mask:0xf bank_mask:0xf bound_ctrl:1
	v_pk_fma_f32 v[48:49], v[142:143], v[42:43], v[48:49] op_sel_hi:[1,0,1]
	v_fmac_f32_e32 v43, v184, v42
	v_pk_fma_f32 v[34:35], v[34:35], v[136:137], v[46:47]
	v_pk_fma_f32 v[36:37], v[36:37], v[138:139], v[48:49]
	v_pk_fma_f32 v[50:51], v[140:141], v[54:55], v[50:51] op_sel_hi:[1,0,1]
	v_pk_fma_f32 v[52:53], v[142:143], v[54:55], v[52:53] op_sel_hi:[1,0,1]
	v_fmac_f32_e32 v43, v176, v185
	v_pk_fma_f32 v[38:39], v[38:39], v[136:137], v[50:51]
	v_pk_fma_f32 v[40:41], v[40:41], v[138:139], v[52:53]
	v_cndmask_b32_e64 v55, 0, v43, s[48:49]
	ds_read_b128 v[132:135], v208 offset:13568
	ds_read_b128 v[136:139], v208 offset:23040
	ds_read_b128 v[140:143], v208 offset:31232
	ds_read_b128 v[144:147], v208 offset:39424
	s_waitcnt lgkmcnt(5)
	v_pk_mul_f32 v[42:43], v[34:35], v[148:149] op_sel_hi:[0,1]
	v_pk_mul_f32 v[44:45], v[38:39], v[148:149] op_sel_hi:[0,1]
	v_pk_fma_f32 v[42:43], v[34:35], v[150:151], v[42:43] op_sel:[1,0,0]
	v_pk_fma_f32 v[44:45], v[38:39], v[150:151], v[44:45] op_sel:[1,0,0]
	v_pk_fma_f32 v[42:43], v[36:37], v[152:153], v[42:43] op_sel_hi:[0,1,1]
	v_pk_fma_f32 v[44:45], v[40:41], v[152:153], v[44:45] op_sel_hi:[0,1,1]
	v_pk_fma_f32 v[42:43], v[36:37], v[154:155], v[42:43] op_sel:[1,0,0]
	v_pk_fma_f32 v[44:45], v[40:41], v[154:155], v[44:45] op_sel:[1,0,0]
	v_pk_mul_f32 v[46:47], v[172:173], v[176:177] op_sel:[0,1]
	v_pk_mul_f32 v[48:49], v[174:175], v[176:177] op_sel:[0,1]
	v_add_f32_dpp v42, v44, v42 quad_perm:[1,0,3,2] row_mask:0xf bank_mask:0xf bound_ctrl:1
	v_add_f32_dpp v43, v45, v43 quad_perm:[1,0,3,2] row_mask:0xf bank_mask:0xf bound_ctrl:1
	v_pk_mul_f32 v[50:51], v[172:173], v[180:181] op_sel:[0,1]
	v_add_f32_dpp v42, v42, v42 quad_perm:[2,3,0,1] row_mask:0xf bank_mask:0xf bound_ctrl:1
	v_add_f32_dpp v43, v43, v43 quad_perm:[2,3,0,1] row_mask:0xf bank_mask:0xf bound_ctrl:1
	v_pk_mul_f32 v[52:53], v[174:175], v[180:181] op_sel:[0,1]
	v_add_f32_dpp v42, v42, v42 row_ror:4 row_mask:0xf bank_mask:0xf bound_ctrl:1
	v_add_f32_dpp v43, v43, v43 row_ror:4 row_mask:0xf bank_mask:0xf bound_ctrl:1
	ds_read_b128 v[148:151], v208 offset:13824
	v_add_f32_dpp v42, v42, v42 row_ror:8 row_mask:0xf bank_mask:0xf bound_ctrl:1
	v_add_f32_dpp v43, v43, v43 row_ror:8 row_mask:0xf bank_mask:0xf bound_ctrl:1
	v_pk_fma_f32 v[46:47], v[168:169], v[42:43], v[46:47] op_sel_hi:[1,0,1]
	v_mov_b32_dpp v54, v42 quad_perm:[1,0,3,2] row_mask:0xf bank_mask:0xf bound_ctrl:1
	v_pk_fma_f32 v[48:49], v[170:171], v[42:43], v[48:49] op_sel_hi:[1,0,1]
	v_fmac_f32_e32 v43, v186, v42
	v_pk_fma_f32 v[34:35], v[34:35], v[156:157], v[46:47]
	v_pk_fma_f32 v[36:37], v[36:37], v[158:159], v[48:49]
	v_pk_fma_f32 v[50:51], v[168:169], v[54:55], v[50:51] op_sel_hi:[1,0,1]
	v_pk_fma_f32 v[52:53], v[170:171], v[54:55], v[52:53] op_sel_hi:[1,0,1]
	v_fmac_f32_e32 v43, v177, v187
	v_pk_fma_f32 v[38:39], v[38:39], v[156:157], v[50:51]
	v_pk_fma_f32 v[40:41], v[40:41], v[158:159], v[52:53]
	v_cndmask_b32_e64 v55, v55, v43, s[50:51]
	ds_read_b128 v[152:155], v208 offset:14080
	ds_read_b128 v[156:159], v208 offset:23296
	ds_read_b128 v[168:171], v208 offset:31488
	ds_read_b128 v[172:175], v208 offset:39680
	ds_read_b128 v[192:195], v209 offset:41072
	ds_read_b128 v[196:199], v210 offset:41072
	ds_read_b128 v[200:203], v211 offset:49888
	ds_read_b128 v[204:207], v211 offset:49904
	s_waitcnt lgkmcnt(9)
	v_pk_mul_f32 v[42:43], v[34:35], v[128:129] op_sel_hi:[0,1]
	v_pk_mul_f32 v[44:45], v[38:39], v[128:129] op_sel_hi:[0,1]
	v_pk_fma_f32 v[42:43], v[34:35], v[130:131], v[42:43] op_sel:[1,0,0]
	v_pk_fma_f32 v[44:45], v[38:39], v[130:131], v[44:45] op_sel:[1,0,0]
	v_pk_fma_f32 v[42:43], v[36:37], v[132:133], v[42:43] op_sel_hi:[0,1,1]
	v_pk_fma_f32 v[44:45], v[40:41], v[132:133], v[44:45] op_sel_hi:[0,1,1]
	v_pk_fma_f32 v[42:43], v[36:37], v[134:135], v[42:43] op_sel:[1,0,0]
	v_pk_fma_f32 v[44:45], v[40:41], v[134:135], v[44:45] op_sel:[1,0,0]
	v_pk_mul_f32 v[46:47], v[144:145], v[178:179] op_sel_hi:[1,0]
	v_pk_mul_f32 v[48:49], v[146:147], v[178:179] op_sel_hi:[1,0]
	v_add_f32_dpp v42, v44, v42 quad_perm:[1,0,3,2] row_mask:0xf bank_mask:0xf bound_ctrl:1
	v_add_f32_dpp v43, v45, v43 quad_perm:[1,0,3,2] row_mask:0xf bank_mask:0xf bound_ctrl:1
	v_pk_mul_f32 v[50:51], v[144:145], v[182:183] op_sel_hi:[1,0]
	v_add_f32_dpp v42, v42, v42 quad_perm:[2,3,0,1] row_mask:0xf bank_mask:0xf bound_ctrl:1
	v_add_f32_dpp v43, v43, v43 quad_perm:[2,3,0,1] row_mask:0xf bank_mask:0xf bound_ctrl:1
	v_pk_mul_f32 v[52:53], v[146:147], v[182:183] op_sel_hi:[1,0]
	v_add_f32_dpp v42, v42, v42 row_ror:4 row_mask:0xf bank_mask:0xf bound_ctrl:1
	v_add_f32_dpp v43, v43, v43 row_ror:4 row_mask:0xf bank_mask:0xf bound_ctrl:1
	ds_read_b128 v[128:131], v208 offset:14336
	v_add_f32_dpp v42, v42, v42 row_ror:8 row_mask:0xf bank_mask:0xf bound_ctrl:1
	v_add_f32_dpp v43, v43, v43 row_ror:8 row_mask:0xf bank_mask:0xf bound_ctrl:1
	v_pk_fma_f32 v[46:47], v[140:141], v[42:43], v[46:47] op_sel_hi:[1,0,1]
	v_mov_b32_dpp v54, v42 quad_perm:[1,0,3,2] row_mask:0xf bank_mask:0xf bound_ctrl:1
	v_pk_fma_f32 v[48:49], v[142:143], v[42:43], v[48:49] op_sel_hi:[1,0,1]
	v_fmac_f32_e32 v43, v188, v42
	v_pk_fma_f32 v[34:35], v[34:35], v[136:137], v[46:47]
	v_pk_fma_f32 v[36:37], v[36:37], v[138:139], v[48:49]
	v_pk_fma_f32 v[50:51], v[140:141], v[54:55], v[50:51] op_sel_hi:[1,0,1]
	v_pk_fma_f32 v[52:53], v[142:143], v[54:55], v[52:53] op_sel_hi:[1,0,1]
	v_fmac_f32_e32 v43, v178, v189
	v_pk_fma_f32 v[38:39], v[38:39], v[136:137], v[50:51]
	v_pk_fma_f32 v[40:41], v[40:41], v[138:139], v[52:53]
	v_cndmask_b32_e64 v55, v55, v43, s[52:53]
	ds_read_b128 v[132:135], v208 offset:14592
	ds_read_b128 v[136:139], v208 offset:23552
	ds_read_b128 v[140:143], v208 offset:31744
	ds_read_b128 v[144:147], v208 offset:39936
	s_waitcnt lgkmcnt(9)
	v_pk_mul_f32 v[42:43], v[34:35], v[148:149] op_sel_hi:[0,1]
	v_pk_mul_f32 v[44:45], v[38:39], v[148:149] op_sel_hi:[0,1]
	v_pk_fma_f32 v[42:43], v[34:35], v[150:151], v[42:43] op_sel:[1,0,0]
	v_pk_fma_f32 v[44:45], v[38:39], v[150:151], v[44:45] op_sel:[1,0,0]
	v_pk_fma_f32 v[42:43], v[36:37], v[152:153], v[42:43] op_sel_hi:[0,1,1]
	v_pk_fma_f32 v[44:45], v[40:41], v[152:153], v[44:45] op_sel_hi:[0,1,1]
	v_pk_fma_f32 v[42:43], v[36:37], v[154:155], v[42:43] op_sel:[1,0,0]
	v_pk_fma_f32 v[44:45], v[40:41], v[154:155], v[44:45] op_sel:[1,0,0]
	v_pk_mul_f32 v[46:47], v[172:173], v[178:179] op_sel:[0,1]
	v_pk_mul_f32 v[48:49], v[174:175], v[178:179] op_sel:[0,1]
	v_add_f32_dpp v42, v44, v42 quad_perm:[1,0,3,2] row_mask:0xf bank_mask:0xf bound_ctrl:1
	v_add_f32_dpp v43, v45, v43 quad_perm:[1,0,3,2] row_mask:0xf bank_mask:0xf bound_ctrl:1
	v_pk_mul_f32 v[50:51], v[172:173], v[182:183] op_sel:[0,1]
	v_add_f32_dpp v42, v42, v42 quad_perm:[2,3,0,1] row_mask:0xf bank_mask:0xf bound_ctrl:1
	v_add_f32_dpp v43, v43, v43 quad_perm:[2,3,0,1] row_mask:0xf bank_mask:0xf bound_ctrl:1
	v_pk_mul_f32 v[52:53], v[174:175], v[182:183] op_sel:[0,1]
	v_add_f32_dpp v42, v42, v42 row_ror:4 row_mask:0xf bank_mask:0xf bound_ctrl:1
	v_add_f32_dpp v43, v43, v43 row_ror:4 row_mask:0xf bank_mask:0xf bound_ctrl:1
	ds_read_b128 v[148:151], v208 offset:14848
	v_add_f32_dpp v42, v42, v42 row_ror:8 row_mask:0xf bank_mask:0xf bound_ctrl:1
	v_add_f32_dpp v43, v43, v43 row_ror:8 row_mask:0xf bank_mask:0xf bound_ctrl:1
	v_pk_fma_f32 v[46:47], v[168:169], v[42:43], v[46:47] op_sel_hi:[1,0,1]
	v_mov_b32_dpp v54, v42 quad_perm:[1,0,3,2] row_mask:0xf bank_mask:0xf bound_ctrl:1
	v_pk_fma_f32 v[48:49], v[170:171], v[42:43], v[48:49] op_sel_hi:[1,0,1]
	v_fmac_f32_e32 v43, v190, v42
	v_pk_fma_f32 v[34:35], v[34:35], v[156:157], v[46:47]
	v_pk_fma_f32 v[36:37], v[36:37], v[158:159], v[48:49]
	v_pk_fma_f32 v[50:51], v[168:169], v[54:55], v[50:51] op_sel_hi:[1,0,1]
	v_pk_fma_f32 v[52:53], v[170:171], v[54:55], v[52:53] op_sel_hi:[1,0,1]
	v_fmac_f32_e32 v43, v179, v191
	v_pk_fma_f32 v[38:39], v[38:39], v[156:157], v[50:51]
	v_pk_fma_f32 v[40:41], v[40:41], v[158:159], v[52:53]
	v_cndmask_b32_e64 v55, v55, v43, s[54:55]
	ds_read_b128 v[152:155], v208 offset:15104
	ds_read_b128 v[156:159], v208 offset:23808
	ds_read_b128 v[168:171], v208 offset:32000
	ds_read_b128 v[172:175], v208 offset:40192
	s_waitcnt lgkmcnt(5)
	v_pk_mul_f32 v[42:43], v[34:35], v[128:129] op_sel_hi:[0,1]
	v_pk_mul_f32 v[44:45], v[38:39], v[128:129] op_sel_hi:[0,1]
	v_pk_fma_f32 v[42:43], v[34:35], v[130:131], v[42:43] op_sel:[1,0,0]
	v_pk_fma_f32 v[44:45], v[38:39], v[130:131], v[44:45] op_sel:[1,0,0]
	v_pk_fma_f32 v[42:43], v[36:37], v[132:133], v[42:43] op_sel_hi:[0,1,1]
	v_pk_fma_f32 v[44:45], v[40:41], v[132:133], v[44:45] op_sel_hi:[0,1,1]
	v_pk_fma_f32 v[42:43], v[36:37], v[134:135], v[42:43] op_sel:[1,0,0]
	v_pk_fma_f32 v[44:45], v[40:41], v[134:135], v[44:45] op_sel:[1,0,0]
	v_pk_mul_f32 v[46:47], v[144:145], v[192:193] op_sel_hi:[1,0]
	v_pk_mul_f32 v[48:49], v[146:147], v[192:193] op_sel_hi:[1,0]
	v_add_f32_dpp v42, v44, v42 quad_perm:[1,0,3,2] row_mask:0xf bank_mask:0xf bound_ctrl:1
	v_add_f32_dpp v43, v45, v43 quad_perm:[1,0,3,2] row_mask:0xf bank_mask:0xf bound_ctrl:1
	v_pk_mul_f32 v[50:51], v[144:145], v[196:197] op_sel_hi:[1,0]
	v_add_f32_dpp v42, v42, v42 quad_perm:[2,3,0,1] row_mask:0xf bank_mask:0xf bound_ctrl:1
	v_add_f32_dpp v43, v43, v43 quad_perm:[2,3,0,1] row_mask:0xf bank_mask:0xf bound_ctrl:1
	v_pk_mul_f32 v[52:53], v[146:147], v[196:197] op_sel_hi:[1,0]
	v_add_f32_dpp v42, v42, v42 row_ror:4 row_mask:0xf bank_mask:0xf bound_ctrl:1
	v_add_f32_dpp v43, v43, v43 row_ror:4 row_mask:0xf bank_mask:0xf bound_ctrl:1
	ds_read_b128 v[128:131], v208 offset:15360
	v_add_f32_dpp v42, v42, v42 row_ror:8 row_mask:0xf bank_mask:0xf bound_ctrl:1
	v_add_f32_dpp v43, v43, v43 row_ror:8 row_mask:0xf bank_mask:0xf bound_ctrl:1
	v_pk_fma_f32 v[46:47], v[140:141], v[42:43], v[46:47] op_sel_hi:[1,0,1]
	v_mov_b32_dpp v54, v42 quad_perm:[1,0,3,2] row_mask:0xf bank_mask:0xf bound_ctrl:1
	v_pk_fma_f32 v[48:49], v[142:143], v[42:43], v[48:49] op_sel_hi:[1,0,1]
	v_fmac_f32_e32 v43, v200, v42
	v_pk_fma_f32 v[34:35], v[34:35], v[136:137], v[46:47]
	v_pk_fma_f32 v[36:37], v[36:37], v[138:139], v[48:49]
	v_pk_fma_f32 v[50:51], v[140:141], v[54:55], v[50:51] op_sel_hi:[1,0,1]
	v_pk_fma_f32 v[52:53], v[142:143], v[54:55], v[52:53] op_sel_hi:[1,0,1]
	v_fmac_f32_e32 v43, v192, v201
	v_pk_fma_f32 v[38:39], v[38:39], v[136:137], v[50:51]
	v_pk_fma_f32 v[40:41], v[40:41], v[138:139], v[52:53]
	v_cndmask_b32_e64 v55, v55, v43, s[56:57]
	ds_read_b128 v[132:135], v208 offset:15616
	ds_read_b128 v[136:139], v208 offset:24064
	ds_read_b128 v[140:143], v208 offset:32256
	ds_read_b128 v[144:147], v208 offset:40448
	s_waitcnt lgkmcnt(5)
	v_pk_mul_f32 v[42:43], v[34:35], v[148:149] op_sel_hi:[0,1]
	v_pk_mul_f32 v[44:45], v[38:39], v[148:149] op_sel_hi:[0,1]
	v_pk_fma_f32 v[42:43], v[34:35], v[150:151], v[42:43] op_sel:[1,0,0]
	v_pk_fma_f32 v[44:45], v[38:39], v[150:151], v[44:45] op_sel:[1,0,0]
	v_pk_fma_f32 v[42:43], v[36:37], v[152:153], v[42:43] op_sel_hi:[0,1,1]
	v_pk_fma_f32 v[44:45], v[40:41], v[152:153], v[44:45] op_sel_hi:[0,1,1]
	v_pk_fma_f32 v[42:43], v[36:37], v[154:155], v[42:43] op_sel:[1,0,0]
	v_pk_fma_f32 v[44:45], v[40:41], v[154:155], v[44:45] op_sel:[1,0,0]
	v_pk_mul_f32 v[46:47], v[172:173], v[192:193] op_sel:[0,1]
	v_pk_mul_f32 v[48:49], v[174:175], v[192:193] op_sel:[0,1]
	v_add_f32_dpp v42, v44, v42 quad_perm:[1,0,3,2] row_mask:0xf bank_mask:0xf bound_ctrl:1
	v_add_f32_dpp v43, v45, v43 quad_perm:[1,0,3,2] row_mask:0xf bank_mask:0xf bound_ctrl:1
	v_pk_mul_f32 v[50:51], v[172:173], v[196:197] op_sel:[0,1]
	v_add_f32_dpp v42, v42, v42 quad_perm:[2,3,0,1] row_mask:0xf bank_mask:0xf bound_ctrl:1
	v_add_f32_dpp v43, v43, v43 quad_perm:[2,3,0,1] row_mask:0xf bank_mask:0xf bound_ctrl:1
	v_pk_mul_f32 v[52:53], v[174:175], v[196:197] op_sel:[0,1]
	v_add_f32_dpp v42, v42, v42 row_ror:4 row_mask:0xf bank_mask:0xf bound_ctrl:1
	v_add_f32_dpp v43, v43, v43 row_ror:4 row_mask:0xf bank_mask:0xf bound_ctrl:1
	ds_read_b128 v[148:151], v208 offset:15872
	v_add_f32_dpp v42, v42, v42 row_ror:8 row_mask:0xf bank_mask:0xf bound_ctrl:1
	v_add_f32_dpp v43, v43, v43 row_ror:8 row_mask:0xf bank_mask:0xf bound_ctrl:1
	v_pk_fma_f32 v[46:47], v[168:169], v[42:43], v[46:47] op_sel_hi:[1,0,1]
	v_mov_b32_dpp v54, v42 quad_perm:[1,0,3,2] row_mask:0xf bank_mask:0xf bound_ctrl:1
	v_pk_fma_f32 v[48:49], v[170:171], v[42:43], v[48:49] op_sel_hi:[1,0,1]
	v_fmac_f32_e32 v43, v202, v42
	v_pk_fma_f32 v[34:35], v[34:35], v[156:157], v[46:47]
	v_pk_fma_f32 v[36:37], v[36:37], v[158:159], v[48:49]
	v_pk_fma_f32 v[50:51], v[168:169], v[54:55], v[50:51] op_sel_hi:[1,0,1]
	v_pk_fma_f32 v[52:53], v[170:171], v[54:55], v[52:53] op_sel_hi:[1,0,1]
	v_fmac_f32_e32 v43, v193, v203
	v_pk_fma_f32 v[38:39], v[38:39], v[156:157], v[50:51]
	v_pk_fma_f32 v[40:41], v[40:41], v[158:159], v[52:53]
	v_cndmask_b32_e64 v55, v55, v43, s[58:59]
	ds_read_b128 v[152:155], v208 offset:16128
	ds_read_b128 v[156:159], v208 offset:24320
	ds_read_b128 v[168:171], v208 offset:32512
	ds_read_b128 v[172:175], v208 offset:40704
	s_waitcnt lgkmcnt(5)
	v_pk_mul_f32 v[42:43], v[34:35], v[128:129] op_sel_hi:[0,1]
	v_pk_mul_f32 v[44:45], v[38:39], v[128:129] op_sel_hi:[0,1]
	v_pk_fma_f32 v[42:43], v[34:35], v[130:131], v[42:43] op_sel:[1,0,0]
	v_pk_fma_f32 v[44:45], v[38:39], v[130:131], v[44:45] op_sel:[1,0,0]
	v_pk_fma_f32 v[42:43], v[36:37], v[132:133], v[42:43] op_sel_hi:[0,1,1]
	v_pk_fma_f32 v[44:45], v[40:41], v[132:133], v[44:45] op_sel_hi:[0,1,1]
	v_pk_fma_f32 v[42:43], v[36:37], v[134:135], v[42:43] op_sel:[1,0,0]
	v_pk_fma_f32 v[44:45], v[40:41], v[134:135], v[44:45] op_sel:[1,0,0]
	v_pk_mul_f32 v[46:47], v[144:145], v[194:195] op_sel_hi:[1,0]
	v_pk_mul_f32 v[48:49], v[146:147], v[194:195] op_sel_hi:[1,0]
	v_add_f32_dpp v42, v44, v42 quad_perm:[1,0,3,2] row_mask:0xf bank_mask:0xf bound_ctrl:1
	v_add_f32_dpp v43, v45, v43 quad_perm:[1,0,3,2] row_mask:0xf bank_mask:0xf bound_ctrl:1
	v_pk_mul_f32 v[50:51], v[144:145], v[198:199] op_sel_hi:[1,0]
	v_add_f32_dpp v42, v42, v42 quad_perm:[2,3,0,1] row_mask:0xf bank_mask:0xf bound_ctrl:1
	v_add_f32_dpp v43, v43, v43 quad_perm:[2,3,0,1] row_mask:0xf bank_mask:0xf bound_ctrl:1
	v_pk_mul_f32 v[52:53], v[146:147], v[198:199] op_sel_hi:[1,0]
	v_add_f32_dpp v42, v42, v42 row_ror:4 row_mask:0xf bank_mask:0xf bound_ctrl:1
	v_add_f32_dpp v43, v43, v43 row_ror:4 row_mask:0xf bank_mask:0xf bound_ctrl:1
	s_nop 0
	v_add_f32_dpp v42, v42, v42 row_ror:8 row_mask:0xf bank_mask:0xf bound_ctrl:1
	v_add_f32_dpp v43, v43, v43 row_ror:8 row_mask:0xf bank_mask:0xf bound_ctrl:1
	v_pk_fma_f32 v[46:47], v[140:141], v[42:43], v[46:47] op_sel_hi:[1,0,1]
	v_mov_b32_dpp v54, v42 quad_perm:[1,0,3,2] row_mask:0xf bank_mask:0xf bound_ctrl:1
	v_pk_fma_f32 v[48:49], v[142:143], v[42:43], v[48:49] op_sel_hi:[1,0,1]
	v_fmac_f32_e32 v43, v204, v42
	v_pk_fma_f32 v[34:35], v[34:35], v[136:137], v[46:47]
	v_pk_fma_f32 v[36:37], v[36:37], v[138:139], v[48:49]
	v_pk_fma_f32 v[50:51], v[140:141], v[54:55], v[50:51] op_sel_hi:[1,0,1]
	v_pk_fma_f32 v[52:53], v[142:143], v[54:55], v[52:53] op_sel_hi:[1,0,1]
	v_fmac_f32_e32 v43, v194, v205
	v_pk_fma_f32 v[38:39], v[38:39], v[136:137], v[50:51]
	v_pk_fma_f32 v[40:41], v[40:41], v[138:139], v[52:53]
	v_cndmask_b32_e64 v55, v55, v43, s[60:61]
	s_waitcnt lgkmcnt(0)
	v_pk_mul_f32 v[42:43], v[34:35], v[148:149] op_sel_hi:[0,1]
	v_pk_mul_f32 v[44:45], v[38:39], v[148:149] op_sel_hi:[0,1]
	v_pk_fma_f32 v[42:43], v[34:35], v[150:151], v[42:43] op_sel:[1,0,0]
	v_pk_fma_f32 v[44:45], v[38:39], v[150:151], v[44:45] op_sel:[1,0,0]
	v_pk_fma_f32 v[42:43], v[36:37], v[152:153], v[42:43] op_sel_hi:[0,1,1]
	v_pk_fma_f32 v[44:45], v[40:41], v[152:153], v[44:45] op_sel_hi:[0,1,1]
	v_pk_fma_f32 v[42:43], v[36:37], v[154:155], v[42:43] op_sel:[1,0,0]
	v_pk_fma_f32 v[44:45], v[40:41], v[154:155], v[44:45] op_sel:[1,0,0]
	v_pk_mul_f32 v[46:47], v[172:173], v[194:195] op_sel:[0,1]
	v_pk_mul_f32 v[48:49], v[174:175], v[194:195] op_sel:[0,1]
	v_add_f32_dpp v42, v44, v42 quad_perm:[1,0,3,2] row_mask:0xf bank_mask:0xf bound_ctrl:1
	v_add_f32_dpp v43, v45, v43 quad_perm:[1,0,3,2] row_mask:0xf bank_mask:0xf bound_ctrl:1
	v_pk_mul_f32 v[50:51], v[172:173], v[198:199] op_sel:[0,1]
	v_add_f32_dpp v42, v42, v42 quad_perm:[2,3,0,1] row_mask:0xf bank_mask:0xf bound_ctrl:1
	v_add_f32_dpp v43, v43, v43 quad_perm:[2,3,0,1] row_mask:0xf bank_mask:0xf bound_ctrl:1
	v_pk_mul_f32 v[52:53], v[174:175], v[198:199] op_sel:[0,1]
	v_add_f32_dpp v42, v42, v42 row_ror:4 row_mask:0xf bank_mask:0xf bound_ctrl:1
	v_add_f32_dpp v43, v43, v43 row_ror:4 row_mask:0xf bank_mask:0xf bound_ctrl:1
	s_nop 0
	v_add_f32_dpp v42, v42, v42 row_ror:8 row_mask:0xf bank_mask:0xf bound_ctrl:1
	v_add_f32_dpp v43, v43, v43 row_ror:8 row_mask:0xf bank_mask:0xf bound_ctrl:1
	v_pk_fma_f32 v[46:47], v[168:169], v[42:43], v[46:47] op_sel_hi:[1,0,1]
	v_mov_b32_dpp v54, v42 quad_perm:[1,0,3,2] row_mask:0xf bank_mask:0xf bound_ctrl:1
	v_pk_fma_f32 v[48:49], v[170:171], v[42:43], v[48:49] op_sel_hi:[1,0,1]
	v_fmac_f32_e32 v43, v206, v42
	v_pk_fma_f32 v[34:35], v[34:35], v[156:157], v[46:47]
	v_pk_fma_f32 v[36:37], v[36:37], v[158:159], v[48:49]
	v_pk_fma_f32 v[50:51], v[168:169], v[54:55], v[50:51] op_sel_hi:[1,0,1]
	v_pk_fma_f32 v[52:53], v[170:171], v[54:55], v[52:53] op_sel_hi:[1,0,1]
	v_fmac_f32_e32 v43, v195, v207
	v_pk_fma_f32 v[38:39], v[38:39], v[156:157], v[50:51]
	v_pk_fma_f32 v[40:41], v[40:41], v[158:159], v[52:53]
	v_cndmask_b32_e64 v55, v55, v43, s[62:63]
	ds_write_b32 v212, v55 offset:3072
	s_setprio 0

.LBB0_813:
	s_andn2_b64 vcc, exec, s[18:19]
	s_cbranch_vccnz .LBB0_834
	s_cmp_lg_u32 s20, 0
	s_cbranch_scc1 .Lscan_l2_consts_done
	v_mov_b32_e32 v210, 0xbfb8aa3b
	v_mov_b32_e32 v211, 1.0
	v_mov_b32_e32 v212, 0x3f1b4598
	v_mul_f32_e32 v204, 0xbfb8aa3b, v90
	v_mul_f32_e32 v205, 0xbfb8aa3b, v91
	v_mul_f32_e32 v206, 0xbfb8aa3b, v94
	v_mul_f32_e32 v207, 0xbfb8aa3b, v92
	v_mul_f32_e32 v208, 0xbfb8aa3b, v93
	v_mul_f32_e32 v209, 0xbfb8aa3b, v95
.Lscan_l2_consts_done:
	s_and_b64 vcc, exec, s[46:47]
	s_cbranch_vccnz .Lscan_l2_layer0
	ds_read_b128 v[42:45], v61
	ds_read_b128 v[50:53], v115
	ds_read_b128 v[46:49], v61 offset:64
	ds_read_b128 v[54:57], v115 offset:64
	ds_read_b128 v[188:191], v119
	ds_read_b128 v[168:171], v116
	ds_read_b128 v[176:179], v117
	ds_read_b128 v[172:175], v116 offset:64
	ds_read_b128 v[180:183], v117 offset:64
	ds_read_b128 v[184:187], v119 offset:1280
	s_waitcnt vmcnt(12) lgkmcnt(9)
	v_mfma_f32_16x16x32_bf16 v[42:45], v[14:17], v[42:45], 0
	s_waitcnt vmcnt(10) lgkmcnt(8)
	v_mfma_f32_16x16x32_bf16 v[50:53], v[18:21], v[50:53], 0
	s_waitcnt lgkmcnt(7)
	v_mfma_f32_16x16x32_bf16 v[46:49], v[22:25], v[46:49], v[42:45]
	s_waitcnt vmcnt(9) lgkmcnt(6)
	v_mfma_f32_16x16x32_bf16 v[50:53], v[26:29], v[54:57], v[50:53]
	s_waitcnt vmcnt(8) lgkmcnt(5)
	v_mfma_f32_16x16x32_bf16 v[42:45], v[30:33], v[188:191], 0
	s_waitcnt lgkmcnt(4)
	v_mfma_f32_16x16x32_bf16 v[192:195], v[14:17], v[168:171], 0
	s_waitcnt lgkmcnt(3)
	v_mfma_f32_16x16x32_bf16 v[200:203], v[18:21], v[176:179], 0
	s_waitcnt lgkmcnt(2)
	v_mfma_f32_16x16x32_bf16 v[196:199], v[22:25], v[172:175], v[192:195]
	s_waitcnt lgkmcnt(1)
	v_mfma_f32_16x16x32_bf16 v[200:203], v[26:29], v[180:183], v[200:203]
	s_waitcnt lgkmcnt(0)
	v_mfma_f32_16x16x32_bf16 v[192:195], v[30:33], v[184:187], 0
	global_load_dwordx4 v[14:17], v[84:85], off offset:-128
	global_load_dwordx4 v[22:25], v[84:85], off offset:-64
	global_load_dwordx4 v[18:21], v[84:85], off
	global_load_dwordx4 v[26:29], v[84:85], off offset:64
	global_load_dwordx4 v[30:33], v[84:85], off offset:128
	v_add_u32_e32 v122, s4, v109
	v_lshl_add_u32 v122, v59, 2, v122
	v_add_u32_e32 v122, v122, v110
	v_add_u32_e32 v123, 64, v122
	v_pk_fma_f32 v[46:47], v[46:47], v[210:211], v[204:205] op_sel:[0,0,0] op_sel_hi:[1,0,0]
	v_pk_fma_f32 v[48:49], v[48:49], v[210:211], v[204:205] op_sel:[0,0,0] op_sel_hi:[1,0,0]
	v_pk_fma_f32 v[50:51], v[50:51], v[210:211], v[204:205] op_sel:[0,0,1] op_sel_hi:[1,0,1]
	v_pk_fma_f32 v[52:53], v[52:53], v[210:211], v[204:205] op_sel:[0,0,1] op_sel_hi:[1,0,1]
	v_pk_fma_f32 v[42:43], v[42:43], v[210:211], v[206:207] op_sel:[0,0,0] op_sel_hi:[1,0,0]
	v_pk_fma_f32 v[44:45], v[44:45], v[210:211], v[206:207] op_sel:[0,0,0] op_sel_hi:[1,0,0]
	v_pk_fma_f32 v[196:197], v[196:197], v[210:211], v[206:207] op_sel:[0,0,1] op_sel_hi:[1,0,1]
	v_pk_fma_f32 v[198:199], v[198:199], v[210:211], v[206:207] op_sel:[0,0,1] op_sel_hi:[1,0,1]
	v_pk_fma_f32 v[200:201], v[200:201], v[210:211], v[208:209] op_sel:[0,0,0] op_sel_hi:[1,0,0]
	v_pk_fma_f32 v[202:203], v[202:203], v[210:211], v[208:209] op_sel:[0,0,0] op_sel_hi:[1,0,0]
	v_pk_fma_f32 v[192:193], v[192:193], v[210:211], v[208:209] op_sel:[0,0,1] op_sel_hi:[1,0,1]
	v_pk_fma_f32 v[194:195], v[194:195], v[210:211], v[208:209] op_sel:[0,0,1] op_sel_hi:[1,0,1]
	v_exp_f32_e32 v46, v46
	v_exp_f32_e32 v47, v47
	v_exp_f32_e32 v48, v48
	v_exp_f32_e32 v49, v49
	v_exp_f32_e32 v50, v50
	v_exp_f32_e32 v51, v51
	v_exp_f32_e32 v52, v52
	v_exp_f32_e32 v53, v53
	v_exp_f32_e32 v42, v42
	v_exp_f32_e32 v43, v43
	v_exp_f32_e32 v44, v44
	v_exp_f32_e32 v45, v45
	v_exp_f32_e32 v196, v196
	v_exp_f32_e32 v197, v197
	v_exp_f32_e32 v198, v198
	v_exp_f32_e32 v199, v199
	v_exp_f32_e32 v200, v200
	v_exp_f32_e32 v201, v201
	v_exp_f32_e32 v202, v202
	v_exp_f32_e32 v203, v203
	v_exp_f32_e32 v192, v192
	v_exp_f32_e32 v193, v193
	v_exp_f32_e32 v194, v194
	v_exp_f32_e32 v195, v195
	v_pk_add_f32 v[46:47], v[46:47], v[210:211] op_sel:[0,1] op_sel_hi:[1,1]
	v_pk_add_f32 v[48:49], v[48:49], v[210:211] op_sel:[0,1] op_sel_hi:[1,1]
	v_pk_add_f32 v[50:51], v[50:51], v[210:211] op_sel:[0,1] op_sel_hi:[1,1]
	v_pk_add_f32 v[52:53], v[52:53], v[210:211] op_sel:[0,1] op_sel_hi:[1,1]
	v_pk_add_f32 v[42:43], v[42:43], v[210:211] op_sel:[0,1] op_sel_hi:[1,1]
	v_pk_add_f32 v[44:45], v[44:45], v[210:211] op_sel:[0,1] op_sel_hi:[1,1]
	v_pk_add_f32 v[196:197], v[196:197], v[210:211] op_sel:[0,1] op_sel_hi:[1,1]
	v_pk_add_f32 v[198:199], v[198:199], v[210:211] op_sel:[0,1] op_sel_hi:[1,1]
	v_pk_add_f32 v[200:201], v[200:201], v[210:211] op_sel:[0,1] op_sel_hi:[1,1]
	v_pk_add_f32 v[202:203], v[202:203], v[210:211] op_sel:[0,1] op_sel_hi:[1,1]
	v_pk_add_f32 v[192:193], v[192:193], v[210:211] op_sel:[0,1] op_sel_hi:[1,1]
	v_pk_add_f32 v[194:195], v[194:195], v[210:211] op_sel:[0,1] op_sel_hi:[1,1]
	v_rcp_f32_e32 v46, v46
	v_rcp_f32_e32 v47, v47
	v_rcp_f32_e32 v48, v48
	v_rcp_f32_e32 v49, v49
	v_rcp_f32_e32 v50, v50
	v_rcp_f32_e32 v51, v51
	v_rcp_f32_e32 v52, v52
	v_rcp_f32_e32 v53, v53
	v_rcp_f32_e32 v42, v42
	v_rcp_f32_e32 v43, v43
	v_rcp_f32_e32 v44, v44
	v_rcp_f32_e32 v45, v45
	v_rcp_f32_e32 v196, v196
	v_rcp_f32_e32 v197, v197
	v_rcp_f32_e32 v198, v198
	v_rcp_f32_e32 v199, v199
	v_rcp_f32_e32 v200, v200
	v_rcp_f32_e32 v201, v201
	v_rcp_f32_e32 v202, v202
	v_rcp_f32_e32 v203, v203
	v_rcp_f32_e32 v192, v192
	v_rcp_f32_e32 v193, v193
	v_rcp_f32_e32 v194, v194
	v_rcp_f32_e32 v195, v195
	v_pk_mul_f32 v[46:47], v[46:47], v[212:213] op_sel_hi:[1,0]
	v_pk_mul_f32 v[48:49], v[48:49], v[212:213] op_sel_hi:[1,0]
	v_pk_mul_f32 v[196:197], v[196:197], v[212:213] op_sel_hi:[1,0]
	v_pk_mul_f32 v[198:199], v[198:199], v[212:213] op_sel_hi:[1,0]
	ds_write2st64_b32 v122, v46, v50 offset0:64 offset1:96
	ds_write2st64_b32 v122, v47, v51 offset0:65 offset1:97
	ds_write2st64_b32 v122, v48, v52 offset0:66 offset1:98
	ds_write2st64_b32 v122, v49, v53 offset0:67 offset1:99
	ds_write_b32 v122, v42 offset:32768
	ds_write_b32 v122, v43 offset:33024
	ds_write_b32 v122, v44 offset:33280
	ds_write_b32 v122, v45 offset:33536
	ds_write2st64_b32 v123, v196, v200 offset0:64 offset1:96
	ds_write2st64_b32 v123, v197, v201 offset0:65 offset1:97
	ds_write2st64_b32 v123, v198, v202 offset0:66 offset1:98
	ds_write2st64_b32 v123, v199, v203 offset0:67 offset1:99
	ds_write_b32 v122, v192 offset:32832
	ds_write_b32 v122, v193 offset:33088
	ds_write_b32 v122, v194 offset:33344
	ds_write_b32 v122, v195 offset:33600
	s_branch .LBB0_834
.Lscan_l2_layer0:
	ds_read_b128 v[42:45], v61
	ds_read_b128 v[50:53], v115
	ds_read_b128 v[46:49], v61 offset:64
	ds_read_b128 v[54:57], v115 offset:64
	ds_read_b128 v[168:171], v116
	ds_read_b128 v[176:179], v117
	ds_read_b128 v[172:175], v116 offset:64
	ds_read_b128 v[180:183], v117 offset:64
	s_waitcnt vmcnt(12) lgkmcnt(7)
	v_mfma_f32_16x16x32_bf16 v[42:45], v[14:17], v[42:45], 0
	s_waitcnt vmcnt(10) lgkmcnt(6)
	v_mfma_f32_16x16x32_bf16 v[50:53], v[18:21], v[50:53], 0
	s_waitcnt lgkmcnt(5)
	v_mfma_f32_16x16x32_bf16 v[46:49], v[22:25], v[46:49], v[42:45]
	s_waitcnt vmcnt(9) lgkmcnt(4)
	v_mfma_f32_16x16x32_bf16 v[50:53], v[26:29], v[54:57], v[50:53]
	s_waitcnt lgkmcnt(3)
	v_mfma_f32_16x16x32_bf16 v[192:195], v[14:17], v[168:171], 0
	s_waitcnt lgkmcnt(2)
	v_mfma_f32_16x16x32_bf16 v[200:203], v[18:21], v[176:179], 0
	s_waitcnt lgkmcnt(1)
	v_mfma_f32_16x16x32_bf16 v[196:199], v[22:25], v[172:175], v[192:195]
	s_waitcnt lgkmcnt(0)
	v_mfma_f32_16x16x32_bf16 v[200:203], v[26:29], v[180:183], v[200:203]
	global_load_dwordx4 v[14:17], v[84:85], off offset:-128
	global_load_dwordx4 v[22:25], v[84:85], off offset:-64
	global_load_dwordx4 v[18:21], v[84:85], off
	global_load_dwordx4 v[26:29], v[84:85], off offset:64
	global_load_dwordx4 v[30:33], v[84:85], off offset:128
	v_add_u32_e32 v122, s4, v109
	v_lshl_add_u32 v122, v59, 2, v122
	v_add_u32_e32 v122, v122, v110
	v_add_u32_e32 v123, 64, v122
	v_pk_fma_f32 v[46:47], v[46:47], v[210:211], v[204:205] op_sel:[0,0,0] op_sel_hi:[1,0,0]
	v_pk_fma_f32 v[48:49], v[48:49], v[210:211], v[204:205] op_sel:[0,0,0] op_sel_hi:[1,0,0]
	v_pk_fma_f32 v[50:51], v[50:51], v[210:211], v[204:205] op_sel:[0,0,1] op_sel_hi:[1,0,1]
	v_pk_fma_f32 v[52:53], v[52:53], v[210:211], v[204:205] op_sel:[0,0,1] op_sel_hi:[1,0,1]
	v_pk_fma_f32 v[196:197], v[196:197], v[210:211], v[206:207] op_sel:[0,0,1] op_sel_hi:[1,0,1]
	v_pk_fma_f32 v[198:199], v[198:199], v[210:211], v[206:207] op_sel:[0,0,1] op_sel_hi:[1,0,1]
	v_pk_fma_f32 v[200:201], v[200:201], v[210:211], v[208:209] op_sel:[0,0,0] op_sel_hi:[1,0,0]
	v_pk_fma_f32 v[202:203], v[202:203], v[210:211], v[208:209] op_sel:[0,0,0] op_sel_hi:[1,0,0]
	v_exp_f32_e32 v46, v46
	v_exp_f32_e32 v47, v47
	v_exp_f32_e32 v48, v48
	v_exp_f32_e32 v49, v49
	v_exp_f32_e32 v50, v50
	v_exp_f32_e32 v51, v51
	v_exp_f32_e32 v52, v52
	v_exp_f32_e32 v53, v53
	v_exp_f32_e32 v196, v196
	v_exp_f32_e32 v197, v197
	v_exp_f32_e32 v198, v198
	v_exp_f32_e32 v199, v199
	v_exp_f32_e32 v200, v200
	v_exp_f32_e32 v201, v201
	v_exp_f32_e32 v202, v202
	v_exp_f32_e32 v203, v203
	v_pk_add_f32 v[46:47], v[46:47], v[210:211] op_sel:[0,1] op_sel_hi:[1,1]
	v_pk_add_f32 v[48:49], v[48:49], v[210:211] op_sel:[0,1] op_sel_hi:[1,1]
	v_pk_add_f32 v[50:51], v[50:51], v[210:211] op_sel:[0,1] op_sel_hi:[1,1]
	v_pk_add_f32 v[52:53], v[52:53], v[210:211] op_sel:[0,1] op_sel_hi:[1,1]
	v_pk_add_f32 v[196:197], v[196:197], v[210:211] op_sel:[0,1] op_sel_hi:[1,1]
	v_pk_add_f32 v[198:199], v[198:199], v[210:211] op_sel:[0,1] op_sel_hi:[1,1]
	v_pk_add_f32 v[200:201], v[200:201], v[210:211] op_sel:[0,1] op_sel_hi:[1,1]
	v_pk_add_f32 v[202:203], v[202:203], v[210:211] op_sel:[0,1] op_sel_hi:[1,1]
	v_rcp_f32_e32 v46, v46
	v_rcp_f32_e32 v47, v47
	v_rcp_f32_e32 v48, v48
	v_rcp_f32_e32 v49, v49
	v_rcp_f32_e32 v50, v50
	v_rcp_f32_e32 v51, v51
	v_rcp_f32_e32 v52, v52
	v_rcp_f32_e32 v53, v53
	v_rcp_f32_e32 v196, v196
	v_rcp_f32_e32 v197, v197
	v_rcp_f32_e32 v198, v198
	v_rcp_f32_e32 v199, v199
	v_rcp_f32_e32 v200, v200
	v_rcp_f32_e32 v201, v201
	v_rcp_f32_e32 v202, v202
	v_rcp_f32_e32 v203, v203
	v_pk_mul_f32 v[46:47], v[46:47], v[212:213] op_sel_hi:[1,0]
	v_pk_mul_f32 v[48:49], v[48:49], v[212:213] op_sel_hi:[1,0]
	v_pk_mul_f32 v[196:197], v[196:197], v[212:213] op_sel_hi:[1,0]
	v_pk_mul_f32 v[198:199], v[198:199], v[212:213] op_sel_hi:[1,0]
	ds_write2st64_b32 v122, v46, v50 offset0:64 offset1:96
	ds_write2st64_b32 v122, v47, v51 offset0:65 offset1:97
	ds_write2st64_b32 v122, v48, v52 offset0:66 offset1:98
	ds_write2st64_b32 v122, v49, v53 offset0:67 offset1:99
	ds_write2st64_b32 v123, v196, v200 offset0:64 offset1:96
	ds_write2st64_b32 v123, v197, v201 offset0:65 offset1:97
	ds_write2st64_b32 v123, v198, v202 offset0:66 offset1:98
	ds_write2st64_b32 v123, v199, v203 offset0:67 offset1:99

.LBB0_1498:
	s_mov_b64 s[0:1], 0
	s_cmp_eq_u32 s74, 20
	s_cbranch_scc1 .LBB0_1552
	v_readlane_b32 s0, v253, 59
	v_readlane_b32 s1, v253, 60
	s_xor_b64 s[4:5], s[0:1], -1
	s_mov_b64 s[0:1], 0
	s_and_b64 vcc, exec, s[4:5]
	s_cbranch_vccz .LBB0_1552
	s_waitcnt vmcnt(0)
	s_waitcnt vmcnt(0) lgkmcnt(0)
	s_barrier
	s_mov_b64 s[0:1], exec
	v_readlane_b32 s4, v252, 5
	v_readlane_b32 s5, v252, 6
	s_and_b64 s[4:5], s[0:1], s[4:5]
	s_mov_b64 exec, s[4:5]
	s_cbranch_execz .LBB0_1551
	v_readlane_b32 s4, v253, 27
	s_waitcnt vmcnt(0) expcnt(0) lgkmcnt(0)
	s_nop 0
	v_mov_b32_e32 v0, s4
	ds_read_b32 v3, v0
	v_readlane_b32 s4, v253, 28
	s_waitcnt lgkmcnt(0)
	v_cmp_ne_u32_e32 vcc, 0, v3
	v_mov_b32_e32 v0, s4
	ds_read_b32 v2, v0
	s_cbranch_vccnz .LBB0_1515
	s_mov_b32 s4, 1
	s_branch .LBB0_1503
